# adds: no-op canonicalize removal in mode-1 hook/epilogue, batched fused-norm slot loads and phase-0 census check loads
# baseline (speedup 1.0000x reference)
; __device__ __forceinline__ float bflo(unsigned u) { return __uint_as_float(u << 16); }
; __device__ __forceinline__ float bfhi(unsigned u) { return __uint_as_float(u & 0xffff0000u); }
; __device__ __forceinline__ float sigratio(float a, float b) { return (1.f + __expf(-fminf(fmaxf(b, -30.f), 30.f))) * __builtin_amdgcn_rcpf(1.f + __expf(-fminf(fmaxf(a, -30.f), 30.f))); }
; #define EPI_SETUP() int ll = l; asm volatile("" : "+s"(ll)); unsigned char* const ws = p.ws; bf16_t* const P = (bf16_t*)(ws + W_PROJ); (void)P; \
;         const float* const MOD = (const float*)(ws + W_MOD) + ll * 12288; (void)MOD; float* const X = (float*)(ws + W_X); (void)X
; #define HOOK_LD(it, bf) do { const int gr = row0 + ((it) >> 2) * 128 + ((it) & 3) * 16; \
;         _Pragma("unroll") for (int bj = 0; bj < 2; ++bj) { gb[bf][bj][0] = *(const u32x4*)(P + pidx(gr, gc0 + bj * 128)); gb[bf][bj][1] = *(const u32x4*)(P + pidx(gr, gc0 + 2048 + bj * 128)); } } while (0)
;     __device__ __forceinline__ void hook(f32x4 (&acc)[2][2][4][2], const pg8::Unit& u, int wr, int wc, int fr, int fq, int which) const {
;         EPI_SETUP();
;         int row0 = u.pm * 256 + wr * 64 + fr; asm volatile("" : "+v"(row0));
;         const int col0 = u.pn * 256 + wc * 32 + 8 * fq;
;         const int gc0 = C_GATE + which * 2048 + col0;
;         u32x4 gb[2][2][2];
;     ...
;         HOOK_LD(0, 0);
; #pragma unroll
;         for (int it = 0; it < 8; ++it) {
;             if (it < 7) HOOK_LD(it + 1, (it + 1) & 1);
;             const int ai = it >> 2, m = it & 3;
; #pragma unroll
;             for (int bj = 0; bj < 2; ++bj) {
;                 const u32x4 ga = gb[it & 1][bj][0], gq = gb[it & 1][bj][1];
; #pragma unroll
;                 for (int n = 0; n < 2; ++n) {
;                     f32x4 r = {sigratio(bflo(ga[2 * n]), bflo(gq[2 * n])), sigratio(bfhi(ga[2 * n]), bfhi(gq[2 * n])), sigratio(bflo(ga[2 * n + 1]), bflo(gq[2 * n + 1])), sigratio(bfhi(ga[2 * n + 1]), bfhi(gq[2 * n + 1]))};
;                     acc[ai][bj][m][n] *= r;
;                 }
;             }
;             asm volatile("" ::: "memory");
.LBB0_208:
	s_cmp_eq_u32 s56, 2
	s_cselect_b64 s[46:47], -1, 0
	s_xor_b64 s[74:75], s[72:73], -1
	s_or_b64 s[46:47], s[74:75], s[46:47]
	s_and_b64 vcc, exec, s[46:47]
	s_cbranch_vccnz .LBB0_203
	s_mov_b32 s3, s24
	v_mov_b32_e32 v132, v2
	v_lshl_add_u32 v3, s56, 11, v0
	v_ashrrev_i32_e32 v133, 31, v132
	v_lshlrev_b64 v[132:133], 8, v[132:133]
	v_lshl_add_u64 v[182:183], v[176:177], 0, v[132:133]
	v_ashrrev_i32_e32 v132, 7, v3
	v_ashrrev_i32_e32 v133, 31, v132
	v_lshlrev_b64 v[186:187], 21, v[132:133]
	v_lshl_add_u64 v[132:133], v[182:183], 0, v[186:187]
	flat_load_dwordx4 v[156:159], v[132:133]
	v_add_u32_e32 v134, 0x800, v3
	v_ashrrev_i32_e32 v132, 7, v134
	v_ashrrev_i32_e32 v133, 31, v132
	v_lshlrev_b64 v[188:189], 21, v[132:133]
	v_lshl_add_u64 v[132:133], v[182:183], 0, v[188:189]
	flat_load_dwordx4 v[160:163], v[132:133]
	v_add_u32_e32 v132, 0x80, v3
	v_ashrrev_i32_e32 v132, 7, v132
	v_ashrrev_i32_e32 v133, 31, v132
	v_lshlrev_b64 v[190:191], 21, v[132:133]
	v_lshl_add_u64 v[132:133], v[182:183], 0, v[190:191]
	flat_load_dwordx4 v[140:143], v[132:133]
	v_add_u32_e32 v3, 0x880, v3
	v_ashrrev_i32_e32 v132, 7, v3
	v_ashrrev_i32_e32 v133, 31, v132
	v_lshlrev_b64 v[192:193], 21, v[132:133]
	v_lshl_add_u64 v[132:133], v[182:183], 0, v[192:193]
	flat_load_dwordx4 v[144:147], v[132:133]
	v_lshl_add_u64 v[136:137], v[182:183], 0, s[34:35]
	v_lshl_add_u64 v[132:133], v[136:137], 0, v[186:187]
	flat_load_dwordx4 v[148:151], v[132:133]
	v_lshl_add_u64 v[132:133], v[136:137], 0, v[188:189]
	flat_load_dwordx4 v[152:155], v[132:133]
	v_lshl_add_u64 v[132:133], v[136:137], 0, v[190:191]
	flat_load_dwordx4 v[132:135], v[132:133]
	v_lshl_add_u64 v[136:137], v[136:137], 0, v[192:193]
	flat_load_dwordx4 v[136:139], v[136:137]
	s_mov_b64 s[46:47], 0x3000
	s_waitcnt vmcnt(0) lgkmcnt(0)
	v_lshlrev_b32_e32 v3, 16, v156
	v_med3_f32 v3, v3, s14, v218
	v_mul_f32_e32 v3, 0xbfb8aa3b, v3
	v_exp_f32_e32 v3, v3
	v_lshlrev_b32_e32 v164, 16, v160
	v_add_f32_e32 v3, 1.0, v3
	v_rcp_f32_e32 v166, v3
	v_and_b32_e32 v3, 0xffff0000, v156
	v_med3_f32 v3, v3, s14, v218
	v_mul_f32_e32 v3, 0xbfb8aa3b, v3
	v_exp_f32_e32 v3, v3
	v_and_b32_e32 v156, 0xffff0000, v160
	v_med3_f32 v156, v156, s14, v218
	v_add_f32_e32 v3, 1.0, v3
	v_rcp_f32_e32 v167, v3
	v_lshlrev_b32_e32 v3, 16, v157
	v_med3_f32 v3, v3, s14, v218
	v_mul_f32_e32 v3, 0xbfb8aa3b, v3
	v_exp_f32_e32 v3, v3
	v_mul_f32_e32 v156, 0xbfb8aa3b, v156
	v_exp_f32_e32 v165, v156
	v_lshlrev_b32_e32 v156, 16, v161
	v_add_f32_e32 v3, 1.0, v3
	v_rcp_f32_e32 v160, v3
	v_and_b32_e32 v3, 0xffff0000, v157
	v_med3_f32 v3, v3, s14, v218
	v_mul_f32_e32 v3, 0xbfb8aa3b, v3
	v_exp_f32_e32 v3, v3
	v_and_b32_e32 v157, 0xffff0000, v161
	v_add_f32_e32 v3, 1.0, v3
	v_rcp_f32_e32 v161, v3
	v_lshlrev_b32_e32 v3, 16, v158
	v_med3_f32 v156, v156, s14, v218
	v_med3_f32 v157, v157, s14, v218
	v_med3_f32 v3, v3, s14, v218
	v_mul_f32_e32 v156, 0xbfb8aa3b, v156
	v_mul_f32_e32 v157, 0xbfb8aa3b, v157
	v_mul_f32_e32 v3, 0xbfb8aa3b, v3
	v_exp_f32_e32 v156, v156
	v_exp_f32_e32 v157, v157
	v_exp_f32_e32 v3, v3
	v_med3_f32 v164, v164, s14, v218
	v_mul_f32_e32 v164, 0xbfb8aa3b, v164
	v_pk_add_f32 v[156:157], v[156:157], 1.0 op_sel_hi:[1,0]
	v_add_f32_e32 v3, 1.0, v3
	v_pk_mul_f32 v[156:157], v[156:157], v[160:161]
	v_rcp_f32_e32 v160, v3
	v_and_b32_e32 v3, 0xffff0000, v158
	v_med3_f32 v3, v3, s14, v218
	v_mul_f32_e32 v3, 0xbfb8aa3b, v3
	v_exp_f32_e32 v3, v3
	v_pk_mul_f32 v[130:131], v[130:131], v[156:157]
	v_lshlrev_b32_e32 v156, 16, v162
	v_and_b32_e32 v157, 0xffff0000, v162
	v_add_f32_e32 v3, 1.0, v3
	v_rcp_f32_e32 v161, v3
	v_lshlrev_b32_e32 v3, 16, v159
	v_med3_f32 v3, v3, s14, v218
	v_mul_f32_e32 v3, 0xbfb8aa3b, v3
	v_exp_f32_e32 v3, v3
	v_lshlrev_b32_e32 v158, 16, v163
	v_med3_f32 v158, v158, s14, v218
	v_add_f32_e32 v3, 1.0, v3
	v_rcp_f32_e32 v162, v3
	v_and_b32_e32 v3, 0xffff0000, v159
	v_med3_f32 v3, v3, s14, v218
	v_mul_f32_e32 v3, 0xbfb8aa3b, v3
	v_exp_f32_e32 v3, v3
	v_and_b32_e32 v159, 0xffff0000, v163
	v_med3_f32 v159, v159, s14, v218
	v_add_f32_e32 v3, 1.0, v3
	v_rcp_f32_e32 v163, v3
	v_lshlrev_b32_e32 v3, 16, v140
	v_mul_f32_e32 v158, 0xbfb8aa3b, v158
	v_mul_f32_e32 v159, 0xbfb8aa3b, v159
	v_med3_f32 v3, v3, s14, v218
	v_exp_f32_e32 v158, v158
	v_exp_f32_e32 v159, v159
	v_mul_f32_e32 v3, 0xbfb8aa3b, v3
	v_exp_f32_e32 v3, v3
	s_nop 0
	v_pk_add_f32 v[158:159], v[158:159], 1.0 op_sel_hi:[1,0]
	v_pk_mul_f32 v[158:159], v[158:159], v[162:163]
	v_add_f32_e32 v3, 1.0, v3
	v_pk_mul_f32 v[126:127], v[126:127], v[158:159]
	v_rcp_f32_e32 v158, v3
	v_and_b32_e32 v3, 0xffff0000, v140
	v_med3_f32 v3, v3, s14, v218
	v_mul_f32_e32 v3, 0xbfb8aa3b, v3
	v_exp_f32_e32 v3, v3
	v_med3_f32 v156, v156, s14, v218
	v_med3_f32 v157, v157, s14, v218
	v_mul_f32_e32 v156, 0xbfb8aa3b, v156
	v_add_f32_e32 v3, 1.0, v3
	v_rcp_f32_e32 v159, v3
	v_lshlrev_b32_e32 v3, 16, v141
	v_mul_f32_e32 v157, 0xbfb8aa3b, v157
	v_med3_f32 v3, v3, s14, v218
	v_exp_f32_e32 v156, v156
	v_exp_f32_e32 v157, v157
	v_mul_f32_e32 v3, 0xbfb8aa3b, v3
	v_exp_f32_e32 v3, v3
	v_and_b32_e32 v140, 0xffff0000, v144
	v_pk_add_f32 v[156:157], v[156:157], 1.0 op_sel_hi:[1,0]
	v_pk_mul_f32 v[156:157], v[156:157], v[160:161]
	v_add_f32_e32 v3, 1.0, v3
	v_pk_mul_f32 v[124:125], v[124:125], v[156:157]
	v_lshlrev_b32_e32 v156, 16, v144
	v_rcp_f32_e32 v144, v3
	v_and_b32_e32 v3, 0xffff0000, v141
	v_med3_f32 v3, v3, s14, v218
	v_mul_f32_e32 v3, 0xbfb8aa3b, v3
	v_exp_f32_e32 v3, v3
	v_med3_f32 v140, v140, s14, v218
	v_mul_f32_e32 v140, 0xbfb8aa3b, v140
	v_exp_f32_e32 v157, v140
	v_add_f32_e32 v3, 1.0, v3
	v_lshlrev_b32_e32 v140, 16, v145
	v_and_b32_e32 v141, 0xffff0000, v145
	v_rcp_f32_e32 v145, v3
	v_lshlrev_b32_e32 v3, 16, v142
; __device__ __forceinline__ float bflo(unsigned u) { return __uint_as_float(u << 16); }
; __device__ __forceinline__ float bfhi(unsigned u) { return __uint_as_float(u & 0xffff0000u); }
; #define HOOK_LD(it, bf) do { const int gr = row0 + ((it) >> 2) * 128 + ((it) & 3) * 16; \
;         _Pragma("unroll") for (int bj = 0; bj < 2; ++bj) { gb[bf][bj][0] = *(const u32x4*)(P + pidx(gr, gc0 + bj * 128)); gb[bf][bj][1] = *(const u32x4*)(P + pidx(gr, gc0 + 2048 + bj * 128)); } } while (0)
; __device__ __forceinline__ float sigratio(float a, float b) { return (1.f + __expf(-fminf(fmaxf(b, -30.f), 30.f))) * __builtin_amdgcn_rcpf(1.f + __expf(-fminf(fmaxf(a, -30.f), 30.f))); }
;     __device__ __forceinline__ void hook(f32x4 (&acc)[2][2][4][2], const pg8::Unit& u, int wr, int wc, int fr, int fq, int which) const {
;     ...
;         HOOK_LD(0, 0);
; #pragma unroll
;         for (int it = 0; it < 8; ++it) {
;             if (it < 7) HOOK_LD(it + 1, (it + 1) & 1);
;             const int ai = it >> 2, m = it & 3;
; #pragma unroll
;             for (int bj = 0; bj < 2; ++bj) {
;                 const u32x4 ga = gb[it & 1][bj][0], gq = gb[it & 1][bj][1];
; #pragma unroll
;                 for (int n = 0; n < 2; ++n) {
;                     f32x4 r = {sigratio(bflo(ga[2 * n]), bflo(gq[2 * n])), sigratio(bfhi(ga[2 * n]), bfhi(gq[2 * n])), sigratio(bflo(ga[2 * n + 1]), bflo(gq[2 * n + 1])), sigratio(bfhi(ga[2 * n + 1]), bfhi(gq[2 * n + 1]))};
;                     acc[ai][bj][m][n] *= r;
;                 }
;             }
;             asm volatile("" ::: "memory");
	v_med3_f32 v140, v140, s14, v218
	v_med3_f32 v141, v141, s14, v218
	v_med3_f32 v3, v3, s14, v218
	v_mul_f32_e32 v140, 0xbfb8aa3b, v140
	v_mul_f32_e32 v141, 0xbfb8aa3b, v141
	v_mul_f32_e32 v3, 0xbfb8aa3b, v3
	v_exp_f32_e32 v140, v140
	v_exp_f32_e32 v141, v141
	v_exp_f32_e32 v3, v3
	v_exp_f32_e32 v164, v164
	s_nop 0
	v_pk_add_f32 v[140:141], v[140:141], 1.0 op_sel_hi:[1,0]
	v_add_f32_e32 v3, 1.0, v3
	v_pk_mul_f32 v[140:141], v[140:141], v[144:145]
	v_rcp_f32_e32 v144, v3
	v_and_b32_e32 v3, 0xffff0000, v142
	v_med3_f32 v3, v3, s14, v218
	v_mul_f32_e32 v3, 0xbfb8aa3b, v3
	v_exp_f32_e32 v3, v3
	v_pk_mul_f32 v[122:123], v[122:123], v[140:141]
	v_lshlrev_b32_e32 v140, 16, v146
	v_and_b32_e32 v141, 0xffff0000, v146
	v_add_f32_e32 v3, 1.0, v3
	v_rcp_f32_e32 v145, v3
	v_lshlrev_b32_e32 v3, 16, v143
	v_med3_f32 v3, v3, s14, v218
	v_mul_f32_e32 v3, 0xbfb8aa3b, v3
	v_exp_f32_e32 v3, v3
	v_lshlrev_b32_e32 v142, 16, v147
	v_pk_add_f32 v[164:165], v[164:165], 1.0 op_sel_hi:[1,0]
	v_add_f32_e32 v3, 1.0, v3
	v_rcp_f32_e32 v146, v3
	v_and_b32_e32 v3, 0xffff0000, v143
	v_med3_f32 v3, v3, s14, v218
	v_mul_f32_e32 v3, 0xbfb8aa3b, v3
	v_exp_f32_e32 v3, v3
	v_and_b32_e32 v143, 0xffff0000, v147
	v_pk_mul_f32 v[164:165], v[164:165], v[166:167]
	v_add_f32_e32 v3, 1.0, v3
	v_rcp_f32_e32 v147, v3
	v_lshlrev_b32_e32 v3, 16, v148
	v_med3_f32 v3, v3, s14, v218
	v_mul_f32_e32 v3, 0xbfb8aa3b, v3
	v_exp_f32_e32 v3, v3
	v_pk_mul_f32 v[128:129], v[128:129], v[164:165]
	v_lshlrev_b32_e32 v164, 16, v152
	v_med3_f32 v140, v140, s14, v218
	v_add_f32_e32 v3, 1.0, v3
	v_rcp_f32_e32 v166, v3
	v_and_b32_e32 v3, 0xffff0000, v148
	v_med3_f32 v3, v3, s14, v218
	v_mul_f32_e32 v3, 0xbfb8aa3b, v3
	v_exp_f32_e32 v3, v3
	v_and_b32_e32 v148, 0xffff0000, v152
	v_med3_f32 v148, v148, s14, v218
	v_add_f32_e32 v3, 1.0, v3
	v_rcp_f32_e32 v167, v3
	v_lshlrev_b32_e32 v3, 16, v149
	v_med3_f32 v3, v3, s14, v218
	v_mul_f32_e32 v3, 0xbfb8aa3b, v3
	v_exp_f32_e32 v3, v3
	v_mul_f32_e32 v148, 0xbfb8aa3b, v148
	v_exp_f32_e32 v165, v148
	v_lshlrev_b32_e32 v148, 16, v153
	v_add_f32_e32 v3, 1.0, v3
	v_rcp_f32_e32 v152, v3
	v_and_b32_e32 v3, 0xffff0000, v149
	v_med3_f32 v3, v3, s14, v218
	v_mul_f32_e32 v3, 0xbfb8aa3b, v3
	v_exp_f32_e32 v3, v3
	v_and_b32_e32 v149, 0xffff0000, v153
	v_add_f32_e32 v3, 1.0, v3
	v_rcp_f32_e32 v153, v3
	v_lshlrev_b32_e32 v3, 16, v150
	v_med3_f32 v148, v148, s14, v218
	v_med3_f32 v149, v149, s14, v218
	v_med3_f32 v3, v3, s14, v218
	v_mul_f32_e32 v148, 0xbfb8aa3b, v148
	v_mul_f32_e32 v149, 0xbfb8aa3b, v149
	v_mul_f32_e32 v3, 0xbfb8aa3b, v3
	v_exp_f32_e32 v148, v148
	v_exp_f32_e32 v149, v149
	v_exp_f32_e32 v3, v3
	v_med3_f32 v141, v141, s14, v218
	v_med3_f32 v156, v156, s14, v218
	v_pk_add_f32 v[148:149], v[148:149], 1.0 op_sel_hi:[1,0]
	v_add_f32_e32 v3, 1.0, v3
	v_pk_mul_f32 v[148:149], v[148:149], v[152:153]
	v_rcp_f32_e32 v152, v3
	v_and_b32_e32 v3, 0xffff0000, v150
	v_med3_f32 v3, v3, s14, v218
	v_mul_f32_e32 v3, 0xbfb8aa3b, v3
	v_exp_f32_e32 v3, v3
	v_mul_f32_e32 v140, 0xbfb8aa3b, v140
	v_mul_f32_e32 v141, 0xbfb8aa3b, v141
	v_mul_f32_e32 v156, 0xbfb8aa3b, v156
	v_add_f32_e32 v3, 1.0, v3
	v_rcp_f32_e32 v153, v3
	v_lshlrev_b32_e32 v3, 16, v151
	v_med3_f32 v3, v3, s14, v218
	v_exp_f32_e32 v140, v140
	v_exp_f32_e32 v141, v141
	v_mul_f32_e32 v3, 0xbfb8aa3b, v3
	v_exp_f32_e32 v156, v156
	v_exp_f32_e32 v3, v3
	v_pk_add_f32 v[140:141], v[140:141], 1.0 op_sel_hi:[1,0]
	v_pk_mul_f32 v[114:115], v[114:115], v[148:149]
	v_pk_add_f32 v[156:157], v[156:157], 1.0 op_sel_hi:[1,0]
	v_pk_mul_f32 v[140:141], v[140:141], v[144:145]
	v_lshl_add_u64 v[144:145], v[182:183], 0, s[68:69]
	v_add_f32_e32 v3, 1.0, v3
	v_pk_mul_f32 v[156:157], v[156:157], v[158:159]
	v_pk_mul_f32 v[116:117], v[116:117], v[140:141]
	v_lshl_add_u64 v[140:141], v[144:145], 0, v[186:187]
	v_lshlrev_b32_e32 v148, 16, v154
	v_and_b32_e32 v149, 0xffff0000, v154
	v_rcp_f32_e32 v154, v3
	v_and_b32_e32 v3, 0xffff0000, v151
	v_pk_mul_f32 v[120:121], v[120:121], v[156:157]
	flat_load_dwordx4 v[156:159], v[140:141]
	v_med3_f32 v3, v3, s14, v218
	v_mul_f32_e32 v3, 0xbfb8aa3b, v3
	v_exp_f32_e32 v3, v3
	v_lshlrev_b32_e32 v150, 16, v155
	v_and_b32_e32 v151, 0xffff0000, v155
	v_add_f32_e32 v3, 1.0, v3
	v_rcp_f32_e32 v155, v3
	v_lshlrev_b32_e32 v3, 16, v132
	v_med3_f32 v150, v150, s14, v218
	v_med3_f32 v151, v151, s14, v218
	v_mul_f32_e32 v150, 0xbfb8aa3b, v150
	v_mul_f32_e32 v151, 0xbfb8aa3b, v151
	v_med3_f32 v3, v3, s14, v218
	v_exp_f32_e32 v150, v150
	v_exp_f32_e32 v151, v151
	v_mul_f32_e32 v3, 0xbfb8aa3b, v3
	v_exp_f32_e32 v3, v3
	v_lshl_add_u64 v[140:141], v[144:145], 0, v[188:189]
	v_pk_add_f32 v[150:151], v[150:151], 1.0 op_sel_hi:[1,0]
	v_pk_mul_f32 v[150:151], v[150:151], v[154:155]
	v_add_f32_e32 v3, 1.0, v3
	v_pk_mul_f32 v[110:111], v[110:111], v[150:151]
	v_rcp_f32_e32 v150, v3
	v_and_b32_e32 v3, 0xffff0000, v132
	v_med3_f32 v3, v3, s14, v218
	v_mul_f32_e32 v3, 0xbfb8aa3b, v3
	v_exp_f32_e32 v3, v3
	s_nop 0
	flat_load_dwordx4 v[160:163], v[140:141]
	v_med3_f32 v148, v148, s14, v218
	v_add_f32_e32 v3, 1.0, v3
	v_rcp_f32_e32 v151, v3
	v_lshlrev_b32_e32 v3, 16, v133
	v_med3_f32 v149, v149, s14, v218
	v_mul_f32_e32 v148, 0xbfb8aa3b, v148
	v_mul_f32_e32 v149, 0xbfb8aa3b, v149
	v_med3_f32 v3, v3, s14, v218
	v_exp_f32_e32 v148, v148
	v_exp_f32_e32 v149, v149
	v_mul_f32_e32 v3, 0xbfb8aa3b, v3
	v_exp_f32_e32 v3, v3
	v_and_b32_e32 v132, 0xffff0000, v136
	v_pk_add_f32 v[148:149], v[148:149], 1.0 op_sel_hi:[1,0]
	v_pk_mul_f32 v[148:149], v[148:149], v[152:153]
	v_add_f32_e32 v3, 1.0, v3
	v_pk_mul_f32 v[108:109], v[108:109], v[148:149]
	v_lshlrev_b32_e32 v148, 16, v136
	v_rcp_f32_e32 v136, v3
	v_and_b32_e32 v3, 0xffff0000, v133
; __device__ __forceinline__ float bflo(unsigned u) { return __uint_as_float(u << 16); }
; __device__ __forceinline__ float bfhi(unsigned u) { return __uint_as_float(u & 0xffff0000u); }
; #define HOOK_LD(it, bf) do { const int gr = row0 + ((it) >> 2) * 128 + ((it) & 3) * 16; \
;         _Pragma("unroll") for (int bj = 0; bj < 2; ++bj) { gb[bf][bj][0] = *(const u32x4*)(P + pidx(gr, gc0 + bj * 128)); gb[bf][bj][1] = *(const u32x4*)(P + pidx(gr, gc0 + 2048 + bj * 128)); } } while (0)
; __device__ __forceinline__ float sigratio(float a, float b) { return (1.f + __expf(-fminf(fmaxf(b, -30.f), 30.f))) * __builtin_amdgcn_rcpf(1.f + __expf(-fminf(fmaxf(a, -30.f), 30.f))); }
;     __device__ __forceinline__ void hook(f32x4 (&acc)[2][2][4][2], const pg8::Unit& u, int wr, int wc, int fr, int fq, int which) const {
;     ...
;         HOOK_LD(0, 0);
; #pragma unroll
;         for (int it = 0; it < 8; ++it) {
;             if (it < 7) HOOK_LD(it + 1, (it + 1) & 1);
;             const int ai = it >> 2, m = it & 3;
; #pragma unroll
;             for (int bj = 0; bj < 2; ++bj) {
;                 const u32x4 ga = gb[it & 1][bj][0], gq = gb[it & 1][bj][1];
; #pragma unroll
;                 for (int n = 0; n < 2; ++n) {
;                     f32x4 r = {sigratio(bflo(ga[2 * n]), bflo(gq[2 * n])), sigratio(bfhi(ga[2 * n]), bfhi(gq[2 * n])), sigratio(bflo(ga[2 * n + 1]), bflo(gq[2 * n + 1])), sigratio(bfhi(ga[2 * n + 1]), bfhi(gq[2 * n + 1]))};
;                     acc[ai][bj][m][n] *= r;
;                 }
;             }
;             asm volatile("" ::: "memory");
	v_med3_f32 v3, v3, s14, v218
	v_mul_f32_e32 v3, 0xbfb8aa3b, v3
	v_exp_f32_e32 v3, v3
	v_med3_f32 v132, v132, s14, v218
	v_mul_f32_e32 v132, 0xbfb8aa3b, v132
	v_exp_f32_e32 v149, v132
	v_add_f32_e32 v3, 1.0, v3
	v_lshlrev_b32_e32 v132, 16, v137
	v_and_b32_e32 v133, 0xffff0000, v137
	v_rcp_f32_e32 v137, v3
	v_lshlrev_b32_e32 v3, 16, v134
	v_med3_f32 v132, v132, s14, v218
	v_med3_f32 v133, v133, s14, v218
	v_med3_f32 v3, v3, s14, v218
	v_mul_f32_e32 v132, 0xbfb8aa3b, v132
	v_mul_f32_e32 v133, 0xbfb8aa3b, v133
	v_mul_f32_e32 v3, 0xbfb8aa3b, v3
	v_exp_f32_e32 v132, v132
	v_exp_f32_e32 v133, v133
	v_exp_f32_e32 v3, v3
	s_nop 0
	v_pk_add_f32 v[132:133], v[132:133], 1.0 op_sel_hi:[1,0]
	v_add_f32_e32 v3, 1.0, v3
	v_pk_mul_f32 v[132:133], v[132:133], v[136:137]
	v_rcp_f32_e32 v136, v3
	v_and_b32_e32 v3, 0xffff0000, v134
	v_med3_f32 v3, v3, s14, v218
	v_mul_f32_e32 v3, 0xbfb8aa3b, v3
	v_exp_f32_e32 v3, v3
	v_med3_f32 v142, v142, s14, v218
	v_med3_f32 v143, v143, s14, v218
	v_mul_f32_e32 v142, 0xbfb8aa3b, v142
	v_add_f32_e32 v3, 1.0, v3
	v_rcp_f32_e32 v137, v3
	v_lshlrev_b32_e32 v3, 16, v135
	v_med3_f32 v3, v3, s14, v218
	v_mul_f32_e32 v143, 0xbfb8aa3b, v143
	v_mul_f32_e32 v3, 0xbfb8aa3b, v3
	v_exp_f32_e32 v142, v142
	v_exp_f32_e32 v143, v143
	v_exp_f32_e32 v3, v3
	v_lshl_add_u64 v[140:141], v[144:145], 0, v[190:191]
	v_pk_mul_f32 v[106:107], v[106:107], v[132:133]
	v_pk_add_f32 v[142:143], v[142:143], 1.0 op_sel_hi:[1,0]
	v_add_f32_e32 v3, 1.0, v3
	v_pk_mul_f32 v[142:143], v[142:143], v[146:147]
	v_lshlrev_b32_e32 v132, 16, v138
	v_and_b32_e32 v133, 0xffff0000, v138
	v_rcp_f32_e32 v138, v3
	v_and_b32_e32 v3, 0xffff0000, v135
	v_pk_mul_f32 v[118:119], v[118:119], v[142:143]
	flat_load_dwordx4 v[140:143], v[140:141]
	v_med3_f32 v3, v3, s14, v218
	v_mul_f32_e32 v3, 0xbfb8aa3b, v3
	v_exp_f32_e32 v3, v3
	v_lshlrev_b32_e32 v134, 16, v139
	v_and_b32_e32 v135, 0xffff0000, v139
	v_add_f32_e32 v3, 1.0, v3
	v_rcp_f32_e32 v139, v3
	s_waitcnt vmcnt(0) lgkmcnt(0)
	v_lshlrev_b32_e32 v3, 16, v156
	v_med3_f32 v134, v134, s14, v218
	v_med3_f32 v135, v135, s14, v218
	v_med3_f32 v3, v3, s14, v218
	v_mul_f32_e32 v134, 0xbfb8aa3b, v134
	v_mul_f32_e32 v135, 0xbfb8aa3b, v135
	v_mul_f32_e32 v3, 0xbfb8aa3b, v3
	v_exp_f32_e32 v134, v134
	v_exp_f32_e32 v135, v135
	v_exp_f32_e32 v3, v3
	s_nop 0
	v_pk_add_f32 v[134:135], v[134:135], 1.0 op_sel_hi:[1,0]
	v_add_f32_e32 v3, 1.0, v3
	v_pk_mul_f32 v[134:135], v[134:135], v[138:139]
	v_rcp_f32_e32 v138, v3
	v_and_b32_e32 v3, 0xffff0000, v156
	v_med3_f32 v3, v3, s14, v218
	v_mul_f32_e32 v3, 0xbfb8aa3b, v3
	v_exp_f32_e32 v3, v3
	v_med3_f32 v132, v132, s14, v218
	v_med3_f32 v133, v133, s14, v218
	v_mul_f32_e32 v132, 0xbfb8aa3b, v132
	v_mul_f32_e32 v133, 0xbfb8aa3b, v133
	v_add_f32_e32 v3, 1.0, v3
	v_lshl_add_u64 v[144:145], v[144:145], 0, v[192:193]
	v_med3_f32 v164, v164, s14, v218
	v_exp_f32_e32 v132, v132
	v_exp_f32_e32 v133, v133
	v_rcp_f32_e32 v139, v3
	v_lshlrev_b32_e32 v3, 16, v157
	flat_load_dwordx4 v[144:147], v[144:145]
	v_mul_f32_e32 v164, 0xbfb8aa3b, v164
	v_med3_f32 v148, v148, s14, v218
	v_exp_f32_e32 v164, v164
	v_mul_f32_e32 v148, 0xbfb8aa3b, v148
	v_med3_f32 v3, v3, s14, v218
	v_exp_f32_e32 v148, v148
	v_mul_f32_e32 v3, 0xbfb8aa3b, v3
	v_pk_add_f32 v[132:133], v[132:133], 1.0 op_sel_hi:[1,0]
	v_exp_f32_e32 v3, v3
	v_pk_mul_f32 v[132:133], v[132:133], v[136:137]
	v_lshl_add_u64 v[136:137], v[182:183], 0, s[46:47]
	v_pk_add_f32 v[164:165], v[164:165], 1.0 op_sel_hi:[1,0]
	v_pk_mul_f32 v[100:101], v[100:101], v[132:133]
	v_lshl_add_u64 v[132:133], v[136:137], 0, v[186:187]
	v_pk_mul_f32 v[164:165], v[164:165], v[166:167]
	v_pk_add_f32 v[148:149], v[148:149], 1.0 op_sel_hi:[1,0]
	flat_load_dwordx4 v[152:155], v[132:133]
	v_lshl_add_u64 v[132:133], v[136:137], 0, v[188:189]
	v_pk_mul_f32 v[112:113], v[112:113], v[164:165]
	v_pk_mul_f32 v[148:149], v[148:149], v[150:151]
	flat_load_dwordx4 v[164:167], v[132:133]
	v_lshl_add_u64 v[132:133], v[136:137], 0, v[190:191]
	v_lshl_add_u64 v[136:137], v[136:137], 0, v[192:193]
	v_add_f32_e32 v3, 1.0, v3
	v_pk_mul_f32 v[104:105], v[104:105], v[148:149]
	v_pk_mul_f32 v[102:103], v[102:103], v[134:135]
	flat_load_dwordx4 v[132:135], v[132:133]
	v_lshlrev_b32_e32 v156, 16, v161
	flat_load_dwordx4 v[148:151], v[136:137]
	v_lshlrev_b32_e32 v136, 16, v160
	v_and_b32_e32 v137, 0xffff0000, v160
	v_rcp_f32_e32 v160, v3
	v_and_b32_e32 v3, 0xffff0000, v157
	v_med3_f32 v3, v3, s14, v218
	v_mul_f32_e32 v3, 0xbfb8aa3b, v3
	v_exp_f32_e32 v3, v3
	v_and_b32_e32 v157, 0xffff0000, v161
	v_add_f32_e32 v3, 1.0, v3
	v_rcp_f32_e32 v161, v3
	v_lshlrev_b32_e32 v3, 16, v158
	v_med3_f32 v136, v136, s14, v218
	v_med3_f32 v137, v137, s14, v218
	v_med3_f32 v156, v156, s14, v218
	v_med3_f32 v157, v157, s14, v218
	v_mul_f32_e32 v136, 0xbfb8aa3b, v136
	v_mul_f32_e32 v137, 0xbfb8aa3b, v137
	v_mul_f32_e32 v156, 0xbfb8aa3b, v156
	v_mul_f32_e32 v157, 0xbfb8aa3b, v157
	v_med3_f32 v3, v3, s14, v218
	v_exp_f32_e32 v136, v136
	v_exp_f32_e32 v137, v137
	v_exp_f32_e32 v156, v156
	v_exp_f32_e32 v157, v157
	v_mul_f32_e32 v3, 0xbfb8aa3b, v3
	v_exp_f32_e32 v3, v3
	v_pk_add_f32 v[136:137], v[136:137], 1.0 op_sel_hi:[1,0]
	v_pk_add_f32 v[156:157], v[156:157], 1.0 op_sel_hi:[1,0]
	v_pk_mul_f32 v[136:137], v[136:137], v[138:139]
	v_pk_mul_f32 v[138:139], v[156:157], v[160:161]
	v_add_f32_e32 v3, 1.0, v3
	v_pk_mul_f32 v[98:99], v[98:99], v[138:139]
	v_rcp_f32_e32 v138, v3
	v_and_b32_e32 v3, 0xffff0000, v158
	v_med3_f32 v3, v3, s14, v218
	v_mul_f32_e32 v3, 0xbfb8aa3b, v3
	v_exp_f32_e32 v3, v3
	v_pk_mul_f32 v[96:97], v[96:97], v[136:137]
	v_lshlrev_b32_e32 v136, 16, v162
	v_and_b32_e32 v137, 0xffff0000, v162
	v_add_f32_e32 v3, 1.0, v3
; __device__ __forceinline__ float bflo(unsigned u) { return __uint_as_float(u << 16); }
; __device__ __forceinline__ float bfhi(unsigned u) { return __uint_as_float(u & 0xffff0000u); }
; #define HOOK_LD(it, bf) do { const int gr = row0 + ((it) >> 2) * 128 + ((it) & 3) * 16; \
;         _Pragma("unroll") for (int bj = 0; bj < 2; ++bj) { gb[bf][bj][0] = *(const u32x4*)(P + pidx(gr, gc0 + bj * 128)); gb[bf][bj][1] = *(const u32x4*)(P + pidx(gr, gc0 + 2048 + bj * 128)); } } while (0)
; __device__ __forceinline__ float sigratio(float a, float b) { return (1.f + __expf(-fminf(fmaxf(b, -30.f), 30.f))) * __builtin_amdgcn_rcpf(1.f + __expf(-fminf(fmaxf(a, -30.f), 30.f))); }
;     __device__ __forceinline__ void hook(f32x4 (&acc)[2][2][4][2], const pg8::Unit& u, int wr, int wc, int fr, int fq, int which) const {
;     ...
;         HOOK_LD(0, 0);
; #pragma unroll
;         for (int it = 0; it < 8; ++it) {
;             if (it < 7) HOOK_LD(it + 1, (it + 1) & 1);
;             const int ai = it >> 2, m = it & 3;
; #pragma unroll
;             for (int bj = 0; bj < 2; ++bj) {
;                 const u32x4 ga = gb[it & 1][bj][0], gq = gb[it & 1][bj][1];
; #pragma unroll
;                 for (int n = 0; n < 2; ++n) {
;                     f32x4 r = {sigratio(bflo(ga[2 * n]), bflo(gq[2 * n])), sigratio(bfhi(ga[2 * n]), bfhi(gq[2 * n])), sigratio(bflo(ga[2 * n + 1]), bflo(gq[2 * n + 1])), sigratio(bfhi(ga[2 * n + 1]), bfhi(gq[2 * n + 1]))};
;                     acc[ai][bj][m][n] *= r;
;                 }
;             }
;             asm volatile("" ::: "memory");
	v_rcp_f32_e32 v139, v3
	v_lshlrev_b32_e32 v3, 16, v159
	v_med3_f32 v3, v3, s14, v218
	v_mul_f32_e32 v3, 0xbfb8aa3b, v3
	v_exp_f32_e32 v3, v3
	v_lshlrev_b32_e32 v156, 16, v163
	v_and_b32_e32 v157, 0xffff0000, v163
	v_add_f32_e32 v3, 1.0, v3
	v_rcp_f32_e32 v158, v3
	v_and_b32_e32 v3, 0xffff0000, v159
	v_med3_f32 v3, v3, s14, v218
	v_mul_f32_e32 v3, 0xbfb8aa3b, v3
	v_exp_f32_e32 v3, v3
	s_nop 0
	v_add_f32_e32 v3, 1.0, v3
	v_rcp_f32_e32 v159, v3
	v_lshlrev_b32_e32 v3, 16, v140
	v_med3_f32 v136, v136, s14, v218
	v_med3_f32 v137, v137, s14, v218
	v_med3_f32 v156, v156, s14, v218
	v_med3_f32 v157, v157, s14, v218
	v_mul_f32_e32 v136, 0xbfb8aa3b, v136
	v_mul_f32_e32 v137, 0xbfb8aa3b, v137
	v_mul_f32_e32 v156, 0xbfb8aa3b, v156
	v_mul_f32_e32 v157, 0xbfb8aa3b, v157
	v_med3_f32 v3, v3, s14, v218
	v_exp_f32_e32 v136, v136
	v_exp_f32_e32 v137, v137
	v_exp_f32_e32 v156, v156
	v_exp_f32_e32 v157, v157
	v_mul_f32_e32 v3, 0xbfb8aa3b, v3
	v_exp_f32_e32 v3, v3
	v_pk_add_f32 v[136:137], v[136:137], 1.0 op_sel_hi:[1,0]
	v_pk_add_f32 v[156:157], v[156:157], 1.0 op_sel_hi:[1,0]
	v_pk_mul_f32 v[136:137], v[136:137], v[138:139]
	v_pk_mul_f32 v[138:139], v[156:157], v[158:159]
	v_add_f32_e32 v3, 1.0, v3
	v_pk_mul_f32 v[94:95], v[94:95], v[138:139]
	v_rcp_f32_e32 v138, v3
	v_and_b32_e32 v3, 0xffff0000, v140
	v_med3_f32 v3, v3, s14, v218
	v_mul_f32_e32 v3, 0xbfb8aa3b, v3
	v_exp_f32_e32 v3, v3
	v_pk_mul_f32 v[92:93], v[92:93], v[136:137]
	s_waitcnt vmcnt(0) lgkmcnt(0)
	v_lshlrev_b32_e32 v136, 16, v144
	v_and_b32_e32 v137, 0xffff0000, v144
	v_add_f32_e32 v3, 1.0, v3
	v_rcp_f32_e32 v139, v3
	v_lshlrev_b32_e32 v3, 16, v141
	v_med3_f32 v3, v3, s14, v218
	v_mul_f32_e32 v3, 0xbfb8aa3b, v3
	v_exp_f32_e32 v3, v3
	v_lshlrev_b32_e32 v140, 16, v145
	v_add_f32_e32 v3, 1.0, v3
	v_rcp_f32_e32 v144, v3
	v_and_b32_e32 v3, 0xffff0000, v141
	v_med3_f32 v3, v3, s14, v218
	v_mul_f32_e32 v3, 0xbfb8aa3b, v3
	v_exp_f32_e32 v3, v3
	v_and_b32_e32 v141, 0xffff0000, v145
	v_add_f32_e32 v3, 1.0, v3
	v_rcp_f32_e32 v145, v3
	v_lshlrev_b32_e32 v3, 16, v142
	v_med3_f32 v136, v136, s14, v218
	v_med3_f32 v137, v137, s14, v218
	v_med3_f32 v140, v140, s14, v218
	v_med3_f32 v141, v141, s14, v218
	v_mul_f32_e32 v136, 0xbfb8aa3b, v136
	v_mul_f32_e32 v137, 0xbfb8aa3b, v137
	v_mul_f32_e32 v140, 0xbfb8aa3b, v140
	v_mul_f32_e32 v141, 0xbfb8aa3b, v141
	v_med3_f32 v3, v3, s14, v218
	v_exp_f32_e32 v136, v136
	v_exp_f32_e32 v137, v137
	v_exp_f32_e32 v140, v140
	v_exp_f32_e32 v141, v141
	v_mul_f32_e32 v3, 0xbfb8aa3b, v3
	v_exp_f32_e32 v3, v3
	v_pk_add_f32 v[136:137], v[136:137], 1.0 op_sel_hi:[1,0]
	v_pk_add_f32 v[140:141], v[140:141], 1.0 op_sel_hi:[1,0]
	v_pk_mul_f32 v[136:137], v[136:137], v[138:139]
	v_pk_mul_f32 v[138:139], v[140:141], v[144:145]
	v_add_f32_e32 v3, 1.0, v3
	v_pk_mul_f32 v[90:91], v[90:91], v[138:139]
	v_rcp_f32_e32 v138, v3
	v_and_b32_e32 v3, 0xffff0000, v142
	v_med3_f32 v3, v3, s14, v218
	v_mul_f32_e32 v3, 0xbfb8aa3b, v3
	v_exp_f32_e32 v3, v3
	v_pk_mul_f32 v[88:89], v[88:89], v[136:137]
	v_lshlrev_b32_e32 v136, 16, v146
	v_and_b32_e32 v137, 0xffff0000, v146
	v_add_f32_e32 v3, 1.0, v3
	v_rcp_f32_e32 v139, v3
	v_lshlrev_b32_e32 v3, 16, v143
	v_med3_f32 v3, v3, s14, v218
	v_mul_f32_e32 v3, 0xbfb8aa3b, v3
	v_exp_f32_e32 v3, v3
	v_lshlrev_b32_e32 v140, 16, v147
	v_and_b32_e32 v141, 0xffff0000, v147
	v_lshlrev_b32_e32 v144, 16, v164
	v_add_f32_e32 v3, 1.0, v3
	v_rcp_f32_e32 v142, v3
	v_and_b32_e32 v3, 0xffff0000, v143
	v_med3_f32 v3, v3, s14, v218
	v_mul_f32_e32 v3, 0xbfb8aa3b, v3
	v_exp_f32_e32 v3, v3
	v_and_b32_e32 v145, 0xffff0000, v164
	v_add_f32_e32 v3, 1.0, v3
	v_rcp_f32_e32 v143, v3
	v_lshlrev_b32_e32 v3, 16, v152
	v_med3_f32 v3, v3, s14, v218
	v_mul_f32_e32 v3, 0xbfb8aa3b, v3
	v_exp_f32_e32 v3, v3
	v_med3_f32 v144, v144, s14, v218
	v_med3_f32 v145, v145, s14, v218
	v_mul_f32_e32 v144, 0xbfb8aa3b, v144
	v_add_f32_e32 v3, 1.0, v3
	v_rcp_f32_e32 v146, v3
	v_and_b32_e32 v3, 0xffff0000, v152
	v_med3_f32 v3, v3, s14, v218
	v_mul_f32_e32 v3, 0xbfb8aa3b, v3
	v_exp_f32_e32 v3, v3
	v_lshlrev_b32_e32 v152, 16, v165
	v_med3_f32 v152, v152, s14, v218
	v_add_f32_e32 v3, 1.0, v3
	v_rcp_f32_e32 v147, v3
	v_lshlrev_b32_e32 v3, 16, v153
	v_med3_f32 v3, v3, s14, v218
	v_mul_f32_e32 v3, 0xbfb8aa3b, v3
	v_exp_f32_e32 v3, v3
	v_mul_f32_e32 v145, 0xbfb8aa3b, v145
	v_mul_f32_e32 v152, 0xbfb8aa3b, v152
	v_exp_f32_e32 v144, v144
	v_add_f32_e32 v3, 1.0, v3
	v_rcp_f32_e32 v164, v3
	v_and_b32_e32 v3, 0xffff0000, v153
	v_med3_f32 v3, v3, s14, v218
	v_mul_f32_e32 v3, 0xbfb8aa3b, v3
	v_exp_f32_e32 v3, v3
	v_and_b32_e32 v153, 0xffff0000, v165
	v_med3_f32 v153, v153, s14, v218
	v_add_f32_e32 v3, 1.0, v3
	v_rcp_f32_e32 v165, v3
	v_lshlrev_b32_e32 v3, 16, v154
	v_mul_f32_e32 v153, 0xbfb8aa3b, v153
	v_med3_f32 v3, v3, s14, v218
	v_exp_f32_e32 v145, v145
	v_exp_f32_e32 v152, v152
	v_exp_f32_e32 v153, v153
	v_mul_f32_e32 v3, 0xbfb8aa3b, v3
	v_exp_f32_e32 v3, v3
	v_pk_add_f32 v[144:145], v[144:145], 1.0 op_sel_hi:[1,0]
	v_pk_add_f32 v[152:153], v[152:153], 1.0 op_sel_hi:[1,0]
	v_pk_mul_f32 v[144:145], v[144:145], v[146:147]
	v_pk_mul_f32 v[146:147], v[152:153], v[164:165]
	v_add_f32_e32 v3, 1.0, v3
	v_pk_mul_f32 v[82:83], v[82:83], v[146:147]
	v_rcp_f32_e32 v146, v3
	v_and_b32_e32 v3, 0xffff0000, v154
	v_med3_f32 v3, v3, s14, v218
	v_mul_f32_e32 v3, 0xbfb8aa3b, v3
	v_exp_f32_e32 v3, v3
	s_nop 0
	v_add_f32_e32 v3, 1.0, v3
	v_rcp_f32_e32 v147, v3
	v_lshlrev_b32_e32 v3, 16, v155
	v_med3_f32 v136, v136, s14, v218
	v_med3_f32 v137, v137, s14, v218
	v_med3_f32 v140, v140, s14, v218
	v_med3_f32 v141, v141, s14, v218
	v_mul_f32_e32 v136, 0xbfb8aa3b, v136
	v_mul_f32_e32 v137, 0xbfb8aa3b, v137
	v_mul_f32_e32 v140, 0xbfb8aa3b, v140
; __device__ __forceinline__ float bflo(unsigned u) { return __uint_as_float(u << 16); }
; __device__ __forceinline__ float bfhi(unsigned u) { return __uint_as_float(u & 0xffff0000u); }
; #define HOOK_LD(it, bf) do { const int gr = row0 + ((it) >> 2) * 128 + ((it) & 3) * 16; \
;         _Pragma("unroll") for (int bj = 0; bj < 2; ++bj) { gb[bf][bj][0] = *(const u32x4*)(P + pidx(gr, gc0 + bj * 128)); gb[bf][bj][1] = *(const u32x4*)(P + pidx(gr, gc0 + 2048 + bj * 128)); } } while (0)
; __device__ __forceinline__ float sigratio(float a, float b) { return (1.f + __expf(-fminf(fmaxf(b, -30.f), 30.f))) * __builtin_amdgcn_rcpf(1.f + __expf(-fminf(fmaxf(a, -30.f), 30.f))); }
;     __device__ __forceinline__ void hook(f32x4 (&acc)[2][2][4][2], const pg8::Unit& u, int wr, int wc, int fr, int fq, int which) const {
;     ...
;         HOOK_LD(0, 0);
; #pragma unroll
;         for (int it = 0; it < 8; ++it) {
;             if (it < 7) HOOK_LD(it + 1, (it + 1) & 1);
;             const int ai = it >> 2, m = it & 3;
; #pragma unroll
;             for (int bj = 0; bj < 2; ++bj) {
;                 const u32x4 ga = gb[it & 1][bj][0], gq = gb[it & 1][bj][1];
; #pragma unroll
;                 for (int n = 0; n < 2; ++n) {
;                     f32x4 r = {sigratio(bflo(ga[2 * n]), bflo(gq[2 * n])), sigratio(bfhi(ga[2 * n]), bfhi(gq[2 * n])), sigratio(bflo(ga[2 * n + 1]), bflo(gq[2 * n + 1])), sigratio(bfhi(ga[2 * n + 1]), bfhi(gq[2 * n + 1]))};
;                     acc[ai][bj][m][n] *= r;
;                 }
;             }
;             asm volatile("" ::: "memory");
	v_mul_f32_e32 v141, 0xbfb8aa3b, v141
	v_med3_f32 v3, v3, s14, v218
	v_exp_f32_e32 v136, v136
	v_exp_f32_e32 v137, v137
	v_exp_f32_e32 v140, v140
	v_exp_f32_e32 v141, v141
	v_mul_f32_e32 v3, 0xbfb8aa3b, v3
	v_exp_f32_e32 v3, v3
	v_pk_add_f32 v[136:137], v[136:137], 1.0 op_sel_hi:[1,0]
	v_pk_add_f32 v[140:141], v[140:141], 1.0 op_sel_hi:[1,0]
	s_mov_b64 s[46:47], 0x8000
	v_pk_mul_f32 v[136:137], v[136:137], v[138:139]
	v_pk_mul_f32 v[138:139], v[140:141], v[142:143]
	v_lshl_add_u64 v[140:141], v[182:183], 0, s[46:47]
	v_add_f32_e32 v3, 1.0, v3
	v_pk_mul_f32 v[84:85], v[84:85], v[136:137]
	v_lshl_add_u64 v[136:137], v[140:141], 0, v[186:187]
	v_rcp_f32_e32 v154, v3
	v_and_b32_e32 v3, 0xffff0000, v155
	flat_load_dwordx4 v[156:159], v[136:137]
	v_med3_f32 v3, v3, s14, v218
	v_mul_f32_e32 v3, 0xbfb8aa3b, v3
	v_exp_f32_e32 v3, v3
	v_pk_mul_f32 v[80:81], v[80:81], v[144:145]
	v_lshlrev_b32_e32 v144, 16, v166
	v_and_b32_e32 v145, 0xffff0000, v166
	v_lshlrev_b32_e32 v152, 16, v167
	v_and_b32_e32 v153, 0xffff0000, v167
	v_add_f32_e32 v3, 1.0, v3
	v_rcp_f32_e32 v155, v3
	v_lshlrev_b32_e32 v3, 16, v132
	v_med3_f32 v144, v144, s14, v218
	v_med3_f32 v145, v145, s14, v218
	v_med3_f32 v152, v152, s14, v218
	v_med3_f32 v153, v153, s14, v218
	v_mul_f32_e32 v144, 0xbfb8aa3b, v144
	v_mul_f32_e32 v145, 0xbfb8aa3b, v145
	v_mul_f32_e32 v152, 0xbfb8aa3b, v152
	v_mul_f32_e32 v153, 0xbfb8aa3b, v153
	v_med3_f32 v3, v3, s14, v218
	v_exp_f32_e32 v144, v144
	v_exp_f32_e32 v145, v145
	v_exp_f32_e32 v152, v152
	v_exp_f32_e32 v153, v153
	v_mul_f32_e32 v3, 0xbfb8aa3b, v3
	v_exp_f32_e32 v3, v3
	v_pk_add_f32 v[144:145], v[144:145], 1.0 op_sel_hi:[1,0]
	v_pk_add_f32 v[152:153], v[152:153], 1.0 op_sel_hi:[1,0]
	v_pk_mul_f32 v[144:145], v[144:145], v[146:147]
	v_pk_mul_f32 v[146:147], v[152:153], v[154:155]
	v_add_f32_e32 v3, 1.0, v3
	v_pk_mul_f32 v[78:79], v[78:79], v[146:147]
	v_rcp_f32_e32 v146, v3
	v_and_b32_e32 v3, 0xffff0000, v132
	v_med3_f32 v3, v3, s14, v218
	v_mul_f32_e32 v3, 0xbfb8aa3b, v3
	v_exp_f32_e32 v3, v3
	v_lshl_add_u64 v[136:137], v[140:141], 0, v[188:189]
	flat_load_dwordx4 v[160:163], v[136:137]
	v_pk_mul_f32 v[76:77], v[76:77], v[144:145]
	v_add_f32_e32 v3, 1.0, v3
	v_rcp_f32_e32 v147, v3
	v_lshlrev_b32_e32 v3, 16, v133
	v_med3_f32 v3, v3, s14, v218
	v_mul_f32_e32 v3, 0xbfb8aa3b, v3
	v_exp_f32_e32 v3, v3
	v_lshlrev_b32_e32 v144, 16, v148
	v_and_b32_e32 v132, 0xffff0000, v148
	v_add_f32_e32 v3, 1.0, v3
	v_rcp_f32_e32 v148, v3
	v_and_b32_e32 v3, 0xffff0000, v133
	v_med3_f32 v3, v3, s14, v218
	v_mul_f32_e32 v3, 0xbfb8aa3b, v3
	v_exp_f32_e32 v3, v3
	v_med3_f32 v132, v132, s14, v218
	v_mul_f32_e32 v132, 0xbfb8aa3b, v132
	v_add_f32_e32 v3, 1.0, v3
	v_exp_f32_e32 v145, v132
	v_lshlrev_b32_e32 v132, 16, v149
	v_and_b32_e32 v133, 0xffff0000, v149
	v_rcp_f32_e32 v149, v3
	v_lshlrev_b32_e32 v3, 16, v134
	v_med3_f32 v144, v144, s14, v218
	v_mul_f32_e32 v144, 0xbfb8aa3b, v144
	v_med3_f32 v3, v3, s14, v218
	v_exp_f32_e32 v144, v144
	v_mul_f32_e32 v3, 0xbfb8aa3b, v3
	v_exp_f32_e32 v3, v3
	v_lshl_add_u64 v[136:137], v[140:141], 0, v[190:191]
	v_pk_add_f32 v[144:145], v[144:145], 1.0 op_sel_hi:[1,0]
	v_pk_mul_f32 v[86:87], v[86:87], v[138:139]
	v_pk_mul_f32 v[144:145], v[144:145], v[146:147]
	v_add_f32_e32 v3, 1.0, v3
	v_pk_mul_f32 v[72:73], v[72:73], v[144:145]
	v_rcp_f32_e32 v144, v3
	v_and_b32_e32 v3, 0xffff0000, v134
	v_med3_f32 v3, v3, s14, v218
	v_mul_f32_e32 v3, 0xbfb8aa3b, v3
	v_exp_f32_e32 v3, v3
	flat_load_dwordx4 v[136:139], v[136:137]
	v_lshl_add_u64 v[140:141], v[140:141], 0, v[192:193]
	flat_load_dwordx4 v[140:143], v[140:141]
	v_add_f32_e32 v3, 1.0, v3
	v_rcp_f32_e32 v145, v3
	v_lshlrev_b32_e32 v3, 16, v135
	v_med3_f32 v3, v3, s14, v218
	v_mul_f32_e32 v3, 0xbfb8aa3b, v3
	v_exp_f32_e32 v3, v3
	s_nop 0
	v_med3_f32 v132, v132, s14, v218
	v_add_f32_e32 v3, 1.0, v3
	v_rcp_f32_e32 v146, v3
	v_and_b32_e32 v3, 0xffff0000, v135
	v_med3_f32 v3, v3, s14, v218
	v_mul_f32_e32 v3, 0xbfb8aa3b, v3
	v_exp_f32_e32 v3, v3
	v_med3_f32 v133, v133, s14, v218
	v_mul_f32_e32 v132, 0xbfb8aa3b, v132
	v_mul_f32_e32 v133, 0xbfb8aa3b, v133
	v_add_f32_e32 v3, 1.0, v3
	v_rcp_f32_e32 v147, v3
	s_waitcnt vmcnt(0) lgkmcnt(0)
	v_lshlrev_b32_e32 v3, 16, v156
	v_med3_f32 v3, v3, s14, v218
	v_mul_f32_e32 v3, 0xbfb8aa3b, v3
	v_exp_f32_e32 v3, v3
	v_exp_f32_e32 v132, v132
	v_exp_f32_e32 v133, v133
	s_mov_b64 s[46:47], 0x9000
	v_add_f32_e32 v3, 1.0, v3
	v_rcp_f32_e32 v154, v3
	v_and_b32_e32 v3, 0xffff0000, v156
	v_med3_f32 v3, v3, s14, v218
	v_mul_f32_e32 v3, 0xbfb8aa3b, v3
	v_exp_f32_e32 v3, v3
	v_lshlrev_b32_e32 v152, 16, v160
	v_and_b32_e32 v153, 0xffff0000, v160
	v_lshlrev_b32_e32 v156, 16, v161
	v_add_f32_e32 v3, 1.0, v3
	v_rcp_f32_e32 v155, v3
	v_lshlrev_b32_e32 v3, 16, v157
	v_med3_f32 v3, v3, s14, v218
	v_mul_f32_e32 v3, 0xbfb8aa3b, v3
	v_exp_f32_e32 v3, v3
	s_nop 0
	v_add_f32_e32 v3, 1.0, v3
	v_rcp_f32_e32 v160, v3
	v_and_b32_e32 v3, 0xffff0000, v157
	v_med3_f32 v3, v3, s14, v218
	v_mul_f32_e32 v3, 0xbfb8aa3b, v3
	v_exp_f32_e32 v3, v3
	v_and_b32_e32 v157, 0xffff0000, v161
	v_med3_f32 v152, v152, s14, v218
	v_add_f32_e32 v3, 1.0, v3
	v_rcp_f32_e32 v161, v3
	v_lshlrev_b32_e32 v3, 16, v158
	v_med3_f32 v153, v153, s14, v218
	v_med3_f32 v156, v156, s14, v218
	v_med3_f32 v157, v157, s14, v218
	v_mul_f32_e32 v152, 0xbfb8aa3b, v152
	v_mul_f32_e32 v153, 0xbfb8aa3b, v153
	v_mul_f32_e32 v156, 0xbfb8aa3b, v156
	v_mul_f32_e32 v157, 0xbfb8aa3b, v157
	v_med3_f32 v3, v3, s14, v218
	v_exp_f32_e32 v152, v152
	v_exp_f32_e32 v153, v153
	v_exp_f32_e32 v156, v156
	v_exp_f32_e32 v157, v157
	v_mul_f32_e32 v3, 0xbfb8aa3b, v3
	v_exp_f32_e32 v3, v3
	v_pk_add_f32 v[152:153], v[152:153], 1.0 op_sel_hi:[1,0]
; __device__ __forceinline__ float bflo(unsigned u) { return __uint_as_float(u << 16); }
; __device__ __forceinline__ float bfhi(unsigned u) { return __uint_as_float(u & 0xffff0000u); }
; #define HOOK_LD(it, bf) do { const int gr = row0 + ((it) >> 2) * 128 + ((it) & 3) * 16; \
;         _Pragma("unroll") for (int bj = 0; bj < 2; ++bj) { gb[bf][bj][0] = *(const u32x4*)(P + pidx(gr, gc0 + bj * 128)); gb[bf][bj][1] = *(const u32x4*)(P + pidx(gr, gc0 + 2048 + bj * 128)); } } while (0)
; __device__ __forceinline__ float sigratio(float a, float b) { return (1.f + __expf(-fminf(fmaxf(b, -30.f), 30.f))) * __builtin_amdgcn_rcpf(1.f + __expf(-fminf(fmaxf(a, -30.f), 30.f))); }
;     __device__ __forceinline__ void hook(f32x4 (&acc)[2][2][4][2], const pg8::Unit& u, int wr, int wc, int fr, int fq, int which) const {
;     ...
;         HOOK_LD(0, 0);
; #pragma unroll
;         for (int it = 0; it < 8; ++it) {
;             if (it < 7) HOOK_LD(it + 1, (it + 1) & 1);
;             const int ai = it >> 2, m = it & 3;
; #pragma unroll
;             for (int bj = 0; bj < 2; ++bj) {
;                 const u32x4 ga = gb[it & 1][bj][0], gq = gb[it & 1][bj][1];
; #pragma unroll
;                 for (int n = 0; n < 2; ++n) {
;                     f32x4 r = {sigratio(bflo(ga[2 * n]), bflo(gq[2 * n])), sigratio(bfhi(ga[2 * n]), bfhi(gq[2 * n])), sigratio(bflo(ga[2 * n + 1]), bflo(gq[2 * n + 1])), sigratio(bfhi(ga[2 * n + 1]), bfhi(gq[2 * n + 1]))};
;                     acc[ai][bj][m][n] *= r;
;                 }
;             }
;             asm volatile("" ::: "memory");
	v_pk_add_f32 v[156:157], v[156:157], 1.0 op_sel_hi:[1,0]
	v_pk_mul_f32 v[152:153], v[152:153], v[154:155]
	v_pk_mul_f32 v[154:155], v[156:157], v[160:161]
	v_add_f32_e32 v3, 1.0, v3
	v_pk_mul_f32 v[66:67], v[66:67], v[154:155]
	v_rcp_f32_e32 v154, v3
	v_and_b32_e32 v3, 0xffff0000, v158
	v_med3_f32 v3, v3, s14, v218
	v_mul_f32_e32 v3, 0xbfb8aa3b, v3
	v_exp_f32_e32 v3, v3
	v_pk_add_f32 v[132:133], v[132:133], 1.0 op_sel_hi:[1,0]
	v_lshlrev_b32_e32 v134, 16, v151
	v_pk_mul_f32 v[132:133], v[132:133], v[148:149]
	v_add_f32_e32 v3, 1.0, v3
	v_pk_mul_f32 v[74:75], v[74:75], v[132:133]
	v_lshlrev_b32_e32 v132, 16, v150
	v_and_b32_e32 v133, 0xffff0000, v150
	v_rcp_f32_e32 v155, v3
	v_lshlrev_b32_e32 v3, 16, v159
	v_med3_f32 v132, v132, s14, v218
	v_med3_f32 v133, v133, s14, v218
	v_mul_f32_e32 v132, 0xbfb8aa3b, v132
	v_mul_f32_e32 v133, 0xbfb8aa3b, v133
	v_med3_f32 v3, v3, s14, v218
	v_exp_f32_e32 v132, v132
	v_exp_f32_e32 v133, v133
	v_mul_f32_e32 v3, 0xbfb8aa3b, v3
	v_exp_f32_e32 v3, v3
	v_and_b32_e32 v135, 0xffff0000, v151
	v_pk_add_f32 v[132:133], v[132:133], 1.0 op_sel_hi:[1,0]
	v_pk_mul_f32 v[64:65], v[64:65], v[152:153]
	v_pk_mul_f32 v[132:133], v[132:133], v[144:145]
	v_lshl_add_u64 v[144:145], v[182:183], 0, s[46:47]
	v_add_f32_e32 v3, 1.0, v3
	v_pk_mul_f32 v[68:69], v[68:69], v[132:133]
	v_lshl_add_u64 v[132:133], v[144:145], 0, v[186:187]
	v_rcp_f32_e32 v158, v3
	v_and_b32_e32 v3, 0xffff0000, v159
	flat_load_dwordx4 v[148:151], v[132:133]
	v_med3_f32 v3, v3, s14, v218
	v_mul_f32_e32 v3, 0xbfb8aa3b, v3
	v_exp_f32_e32 v3, v3
	v_lshlrev_b32_e32 v152, 16, v162
	v_and_b32_e32 v153, 0xffff0000, v162
	v_lshlrev_b32_e32 v156, 16, v163
	v_and_b32_e32 v157, 0xffff0000, v163
	v_add_f32_e32 v3, 1.0, v3
	v_rcp_f32_e32 v159, v3
	v_lshlrev_b32_e32 v3, 16, v136
	v_med3_f32 v152, v152, s14, v218
	v_med3_f32 v153, v153, s14, v218
	v_med3_f32 v156, v156, s14, v218
	v_med3_f32 v157, v157, s14, v218
	v_mul_f32_e32 v152, 0xbfb8aa3b, v152
	v_mul_f32_e32 v153, 0xbfb8aa3b, v153
	v_mul_f32_e32 v156, 0xbfb8aa3b, v156
	v_mul_f32_e32 v157, 0xbfb8aa3b, v157
	v_med3_f32 v3, v3, s14, v218
	v_exp_f32_e32 v152, v152
	v_exp_f32_e32 v153, v153
	v_exp_f32_e32 v156, v156
	v_exp_f32_e32 v157, v157
	v_mul_f32_e32 v3, 0xbfb8aa3b, v3
	v_exp_f32_e32 v3, v3
	v_pk_add_f32 v[152:153], v[152:153], 1.0 op_sel_hi:[1,0]
	v_pk_add_f32 v[156:157], v[156:157], 1.0 op_sel_hi:[1,0]
	v_pk_mul_f32 v[152:153], v[152:153], v[154:155]
	v_pk_mul_f32 v[154:155], v[156:157], v[158:159]
	v_add_f32_e32 v3, 1.0, v3
	v_pk_mul_f32 v[62:63], v[62:63], v[154:155]
	v_rcp_f32_e32 v154, v3
	v_and_b32_e32 v3, 0xffff0000, v136
	v_med3_f32 v3, v3, s14, v218
	v_mul_f32_e32 v3, 0xbfb8aa3b, v3
	v_exp_f32_e32 v3, v3
	v_lshl_add_u64 v[132:133], v[144:145], 0, v[188:189]
	flat_load_dwordx4 v[164:167], v[132:133]
	v_pk_mul_f32 v[60:61], v[60:61], v[152:153]
	v_add_f32_e32 v3, 1.0, v3
	v_rcp_f32_e32 v155, v3
	v_lshlrev_b32_e32 v3, 16, v137
	v_med3_f32 v3, v3, s14, v218
	v_mul_f32_e32 v3, 0xbfb8aa3b, v3
	v_exp_f32_e32 v3, v3
	v_lshlrev_b32_e32 v152, 16, v140
	v_and_b32_e32 v136, 0xffff0000, v140
	v_add_f32_e32 v3, 1.0, v3
	v_rcp_f32_e32 v140, v3
	v_and_b32_e32 v3, 0xffff0000, v137
	v_med3_f32 v3, v3, s14, v218
	v_mul_f32_e32 v3, 0xbfb8aa3b, v3
	v_exp_f32_e32 v3, v3
	v_med3_f32 v136, v136, s14, v218
	v_mul_f32_e32 v136, 0xbfb8aa3b, v136
	v_exp_f32_e32 v153, v136
	v_add_f32_e32 v3, 1.0, v3
	v_lshlrev_b32_e32 v136, 16, v141
	v_and_b32_e32 v137, 0xffff0000, v141
	v_rcp_f32_e32 v141, v3
	v_lshlrev_b32_e32 v3, 16, v138
	v_med3_f32 v136, v136, s14, v218
	v_med3_f32 v137, v137, s14, v218
	v_med3_f32 v3, v3, s14, v218
	v_mul_f32_e32 v136, 0xbfb8aa3b, v136
	v_mul_f32_e32 v137, 0xbfb8aa3b, v137
	v_mul_f32_e32 v3, 0xbfb8aa3b, v3
	v_exp_f32_e32 v136, v136
	v_exp_f32_e32 v137, v137
	v_exp_f32_e32 v3, v3
	s_nop 0
	v_pk_add_f32 v[136:137], v[136:137], 1.0 op_sel_hi:[1,0]
	v_add_f32_e32 v3, 1.0, v3
	v_pk_mul_f32 v[136:137], v[136:137], v[140:141]
	v_rcp_f32_e32 v140, v3
	v_and_b32_e32 v3, 0xffff0000, v138
	v_med3_f32 v3, v3, s14, v218
	v_mul_f32_e32 v3, 0xbfb8aa3b, v3
	v_exp_f32_e32 v3, v3
	v_med3_f32 v134, v134, s14, v218
	v_med3_f32 v135, v135, s14, v218
	v_mul_f32_e32 v134, 0xbfb8aa3b, v134
	v_add_f32_e32 v3, 1.0, v3
	v_rcp_f32_e32 v141, v3
	v_lshlrev_b32_e32 v3, 16, v139
	v_med3_f32 v3, v3, s14, v218
	v_mul_f32_e32 v135, 0xbfb8aa3b, v135
	v_mul_f32_e32 v3, 0xbfb8aa3b, v3
	v_exp_f32_e32 v134, v134
	v_exp_f32_e32 v135, v135
	v_exp_f32_e32 v3, v3
	v_lshl_add_u64 v[132:133], v[144:145], 0, v[190:191]
	v_pk_mul_f32 v[58:59], v[58:59], v[136:137]
	v_pk_add_f32 v[134:135], v[134:135], 1.0 op_sel_hi:[1,0]
	v_add_f32_e32 v3, 1.0, v3
	v_pk_mul_f32 v[134:135], v[134:135], v[146:147]
	v_lshlrev_b32_e32 v136, 16, v142
	v_and_b32_e32 v137, 0xffff0000, v142
	v_rcp_f32_e32 v142, v3
	v_and_b32_e32 v3, 0xffff0000, v139
	v_pk_mul_f32 v[70:71], v[70:71], v[134:135]
	flat_load_dwordx4 v[132:135], v[132:133]
	v_med3_f32 v3, v3, s14, v218
	v_mul_f32_e32 v3, 0xbfb8aa3b, v3
	v_exp_f32_e32 v3, v3
	v_lshlrev_b32_e32 v138, 16, v143
	v_and_b32_e32 v139, 0xffff0000, v143
	v_lshl_add_u64 v[144:145], v[144:145], 0, v[192:193]
	v_add_f32_e32 v3, 1.0, v3
	v_rcp_f32_e32 v143, v3
	s_waitcnt vmcnt(0) lgkmcnt(0)
; __device__ __forceinline__ float bflo(unsigned u) { return __uint_as_float(u << 16); }
; __device__ __forceinline__ float bfhi(unsigned u) { return __uint_as_float(u & 0xffff0000u); }
; #define HOOK_LD(it, bf) do { const int gr = row0 + ((it) >> 2) * 128 + ((it) & 3) * 16; \
;         _Pragma("unroll") for (int bj = 0; bj < 2; ++bj) { gb[bf][bj][0] = *(const u32x4*)(P + pidx(gr, gc0 + bj * 128)); gb[bf][bj][1] = *(const u32x4*)(P + pidx(gr, gc0 + 2048 + bj * 128)); } } while (0)
; __device__ __forceinline__ float sigratio(float a, float b) { return (1.f + __expf(-fminf(fmaxf(b, -30.f), 30.f))) * __builtin_amdgcn_rcpf(1.f + __expf(-fminf(fmaxf(a, -30.f), 30.f))); }
;     __device__ __forceinline__ void hook(f32x4 (&acc)[2][2][4][2], const pg8::Unit& u, int wr, int wc, int fr, int fq, int which) const {
;     ...
;         HOOK_LD(0, 0);
; #pragma unroll
;         for (int it = 0; it < 8; ++it) {
;             if (it < 7) HOOK_LD(it + 1, (it + 1) & 1);
;             const int ai = it >> 2, m = it & 3;
; #pragma unroll
;             for (int bj = 0; bj < 2; ++bj) {
;                 const u32x4 ga = gb[it & 1][bj][0], gq = gb[it & 1][bj][1];
; #pragma unroll
;                 for (int n = 0; n < 2; ++n) {
;                     f32x4 r = {sigratio(bflo(ga[2 * n]), bflo(gq[2 * n])), sigratio(bfhi(ga[2 * n]), bfhi(gq[2 * n])), sigratio(bflo(ga[2 * n + 1]), bflo(gq[2 * n + 1])), sigratio(bfhi(ga[2 * n + 1]), bfhi(gq[2 * n + 1]))};
;                     acc[ai][bj][m][n] *= r;
;                 }
;             }
;             asm volatile("" ::: "memory");
	v_lshlrev_b32_e32 v3, 16, v148
	v_med3_f32 v3, v3, s14, v218
	v_mul_f32_e32 v3, 0xbfb8aa3b, v3
	v_exp_f32_e32 v3, v3
	flat_load_dwordx4 v[144:147], v[144:145]
	v_lshlrev_b32_e32 v160, 16, v164
	v_add_f32_e32 v3, 1.0, v3
	v_rcp_f32_e32 v162, v3
	v_and_b32_e32 v3, 0xffff0000, v148
	v_med3_f32 v3, v3, s14, v218
	v_mul_f32_e32 v3, 0xbfb8aa3b, v3
	v_exp_f32_e32 v3, v3
	v_and_b32_e32 v148, 0xffff0000, v164
	v_med3_f32 v148, v148, s14, v218
	v_add_f32_e32 v3, 1.0, v3
	v_rcp_f32_e32 v163, v3
	v_lshlrev_b32_e32 v3, 16, v149
	v_med3_f32 v3, v3, s14, v218
	v_mul_f32_e32 v3, 0xbfb8aa3b, v3
	v_exp_f32_e32 v3, v3
	v_mul_f32_e32 v148, 0xbfb8aa3b, v148
	v_exp_f32_e32 v161, v148
	v_lshlrev_b32_e32 v148, 16, v165
	v_add_f32_e32 v3, 1.0, v3
	v_rcp_f32_e32 v164, v3
	v_and_b32_e32 v3, 0xffff0000, v149
	v_med3_f32 v3, v3, s14, v218
	v_mul_f32_e32 v3, 0xbfb8aa3b, v3
	v_exp_f32_e32 v3, v3
	v_and_b32_e32 v149, 0xffff0000, v165
	v_med3_f32 v160, v160, s14, v218
	v_mul_f32_e32 v160, 0xbfb8aa3b, v160
	v_add_f32_e32 v3, 1.0, v3
	v_rcp_f32_e32 v165, v3
	v_lshlrev_b32_e32 v3, 16, v150
	v_med3_f32 v3, v3, s14, v218
	v_exp_f32_e32 v160, v160
	v_mul_f32_e32 v3, 0xbfb8aa3b, v3
	v_exp_f32_e32 v3, v3
	s_nop 0
	v_pk_add_f32 v[160:161], v[160:161], 1.0 op_sel_hi:[1,0]
	v_pk_mul_f32 v[160:161], v[160:161], v[162:163]
	v_add_f32_e32 v3, 1.0, v3
	v_pk_mul_f32 v[48:49], v[48:49], v[160:161]
	v_rcp_f32_e32 v160, v3
	v_and_b32_e32 v3, 0xffff0000, v150
	v_med3_f32 v3, v3, s14, v218
	v_mul_f32_e32 v3, 0xbfb8aa3b, v3
	v_exp_f32_e32 v3, v3
	s_nop 0
	v_med3_f32 v136, v136, s14, v218
	v_med3_f32 v137, v137, s14, v218
	v_add_f32_e32 v3, 1.0, v3
	v_rcp_f32_e32 v161, v3
	v_lshlrev_b32_e32 v3, 16, v151
	v_med3_f32 v152, v152, s14, v218
	v_mul_f32_e32 v136, 0xbfb8aa3b, v136
	v_mul_f32_e32 v137, 0xbfb8aa3b, v137
	v_med3_f32 v3, v3, s14, v218
	v_mul_f32_e32 v152, 0xbfb8aa3b, v152
	v_exp_f32_e32 v136, v136
	v_exp_f32_e32 v137, v137
	v_mul_f32_e32 v3, 0xbfb8aa3b, v3
	v_exp_f32_e32 v152, v152
	v_exp_f32_e32 v3, v3
	v_pk_add_f32 v[136:137], v[136:137], 1.0 op_sel_hi:[1,0]
	s_mov_b64 s[46:47], 0xa000
	v_pk_add_f32 v[152:153], v[152:153], 1.0 op_sel_hi:[1,0]
	v_pk_mul_f32 v[136:137], v[136:137], v[140:141]
	v_lshl_add_u64 v[140:141], v[182:183], 0, s[46:47]
	v_add_f32_e32 v3, 1.0, v3
	v_pk_mul_f32 v[152:153], v[152:153], v[154:155]
	v_pk_mul_f32 v[52:53], v[52:53], v[136:137]
	v_lshl_add_u64 v[136:137], v[140:141], 0, v[186:187]
	v_rcp_f32_e32 v162, v3
	v_and_b32_e32 v3, 0xffff0000, v151
	v_pk_mul_f32 v[56:57], v[56:57], v[152:153]
	flat_load_dwordx4 v[152:155], v[136:137]
	v_med3_f32 v3, v3, s14, v218
	v_mul_f32_e32 v3, 0xbfb8aa3b, v3
	v_exp_f32_e32 v3, v3
	v_lshlrev_b32_e32 v150, 16, v167
	v_and_b32_e32 v151, 0xffff0000, v167
	v_add_f32_e32 v3, 1.0, v3
	v_rcp_f32_e32 v163, v3
	v_lshlrev_b32_e32 v3, 16, v132
	v_med3_f32 v150, v150, s14, v218
	v_med3_f32 v151, v151, s14, v218
	v_mul_f32_e32 v150, 0xbfb8aa3b, v150
	v_mul_f32_e32 v151, 0xbfb8aa3b, v151
	v_med3_f32 v3, v3, s14, v218
	v_exp_f32_e32 v150, v150
	v_exp_f32_e32 v151, v151
	v_mul_f32_e32 v3, 0xbfb8aa3b, v3
	v_exp_f32_e32 v3, v3
	s_nop 0
	v_pk_add_f32 v[150:151], v[150:151], 1.0 op_sel_hi:[1,0]
	v_pk_mul_f32 v[150:151], v[150:151], v[162:163]
	v_add_f32_e32 v3, 1.0, v3
	v_med3_f32 v148, v148, s14, v218
	v_med3_f32 v149, v149, s14, v218
	v_pk_mul_f32 v[46:47], v[46:47], v[150:151]
	v_rcp_f32_e32 v150, v3
	v_and_b32_e32 v3, 0xffff0000, v132
	v_mul_f32_e32 v148, 0xbfb8aa3b, v148
	v_mul_f32_e32 v149, 0xbfb8aa3b, v149
	v_exp_f32_e32 v148, v148
	v_exp_f32_e32 v149, v149
	v_med3_f32 v3, v3, s14, v218
	v_mul_f32_e32 v3, 0xbfb8aa3b, v3
	v_exp_f32_e32 v3, v3
	v_pk_add_f32 v[148:149], v[148:149], 1.0 op_sel_hi:[1,0]
	v_lshl_add_u64 v[136:137], v[140:141], 0, v[188:189]
	v_pk_mul_f32 v[148:149], v[148:149], v[164:165]
	v_add_f32_e32 v3, 1.0, v3
	v_pk_mul_f32 v[50:51], v[50:51], v[148:149]
	v_lshlrev_b32_e32 v148, 16, v166
	v_and_b32_e32 v149, 0xffff0000, v166
	v_rcp_f32_e32 v151, v3
	v_lshlrev_b32_e32 v3, 16, v133
	flat_load_dwordx4 v[156:159], v[136:137]
	v_med3_f32 v148, v148, s14, v218
	v_med3_f32 v149, v149, s14, v218
	v_mul_f32_e32 v148, 0xbfb8aa3b, v148
	v_mul_f32_e32 v149, 0xbfb8aa3b, v149
	v_med3_f32 v3, v3, s14, v218
	v_exp_f32_e32 v148, v148
	v_exp_f32_e32 v149, v149
	v_mul_f32_e32 v3, 0xbfb8aa3b, v3
	v_exp_f32_e32 v3, v3
	s_waitcnt vmcnt(0) lgkmcnt(0)
; __device__ __forceinline__ float bflo(unsigned u) { return __uint_as_float(u << 16); }
; __device__ __forceinline__ float bfhi(unsigned u) { return __uint_as_float(u & 0xffff0000u); }
; #define HOOK_LD(it, bf) do { const int gr = row0 + ((it) >> 2) * 128 + ((it) & 3) * 16; \
;         _Pragma("unroll") for (int bj = 0; bj < 2; ++bj) { gb[bf][bj][0] = *(const u32x4*)(P + pidx(gr, gc0 + bj * 128)); gb[bf][bj][1] = *(const u32x4*)(P + pidx(gr, gc0 + 2048 + bj * 128)); } } while (0)
; __device__ __forceinline__ float sigratio(float a, float b) { return (1.f + __expf(-fminf(fmaxf(b, -30.f), 30.f))) * __builtin_amdgcn_rcpf(1.f + __expf(-fminf(fmaxf(a, -30.f), 30.f))); }
;     __device__ __forceinline__ void hook(f32x4 (&acc)[2][2][4][2], const pg8::Unit& u, int wr, int wc, int fr, int fq, int which) const {
;     ...
;         HOOK_LD(0, 0);
; #pragma unroll
;         for (int it = 0; it < 8; ++it) {
;             if (it < 7) HOOK_LD(it + 1, (it + 1) & 1);
;             const int ai = it >> 2, m = it & 3;
; #pragma unroll
;             for (int bj = 0; bj < 2; ++bj) {
;                 const u32x4 ga = gb[it & 1][bj][0], gq = gb[it & 1][bj][1];
; #pragma unroll
;                 for (int n = 0; n < 2; ++n) {
;                     f32x4 r = {sigratio(bflo(ga[2 * n]), bflo(gq[2 * n])), sigratio(bfhi(ga[2 * n]), bfhi(gq[2 * n])), sigratio(bflo(ga[2 * n + 1]), bflo(gq[2 * n + 1])), sigratio(bfhi(ga[2 * n + 1]), bfhi(gq[2 * n + 1]))};
;                     acc[ai][bj][m][n] *= r;
;                 }
;             }
;             asm volatile("" ::: "memory");
	v_and_b32_e32 v132, 0xffff0000, v144
	v_pk_add_f32 v[148:149], v[148:149], 1.0 op_sel_hi:[1,0]
	v_pk_mul_f32 v[148:149], v[148:149], v[160:161]
	v_add_f32_e32 v3, 1.0, v3
	v_pk_mul_f32 v[44:45], v[44:45], v[148:149]
	v_lshlrev_b32_e32 v148, 16, v144
	v_rcp_f32_e32 v144, v3
	v_and_b32_e32 v3, 0xffff0000, v133
	v_med3_f32 v3, v3, s14, v218
	v_mul_f32_e32 v3, 0xbfb8aa3b, v3
	v_exp_f32_e32 v3, v3
	v_med3_f32 v132, v132, s14, v218
	v_mul_f32_e32 v132, 0xbfb8aa3b, v132
	v_exp_f32_e32 v149, v132
	v_add_f32_e32 v3, 1.0, v3
	v_lshlrev_b32_e32 v132, 16, v145
	v_and_b32_e32 v133, 0xffff0000, v145
	v_rcp_f32_e32 v145, v3
	v_lshlrev_b32_e32 v3, 16, v134
	v_med3_f32 v132, v132, s14, v218
	v_med3_f32 v133, v133, s14, v218
	v_med3_f32 v3, v3, s14, v218
	v_mul_f32_e32 v132, 0xbfb8aa3b, v132
	v_mul_f32_e32 v133, 0xbfb8aa3b, v133
	v_mul_f32_e32 v3, 0xbfb8aa3b, v3
	v_exp_f32_e32 v132, v132
	v_exp_f32_e32 v133, v133
	v_exp_f32_e32 v3, v3
	s_nop 0
	v_pk_add_f32 v[132:133], v[132:133], 1.0 op_sel_hi:[1,0]
	v_add_f32_e32 v3, 1.0, v3
	v_pk_mul_f32 v[132:133], v[132:133], v[144:145]
	v_rcp_f32_e32 v144, v3
	v_and_b32_e32 v3, 0xffff0000, v134
	v_med3_f32 v3, v3, s14, v218
	v_mul_f32_e32 v3, 0xbfb8aa3b, v3
	v_exp_f32_e32 v3, v3
	v_med3_f32 v138, v138, s14, v218
	v_med3_f32 v139, v139, s14, v218
	v_mul_f32_e32 v138, 0xbfb8aa3b, v138
	v_add_f32_e32 v3, 1.0, v3
	v_rcp_f32_e32 v145, v3
	v_lshlrev_b32_e32 v3, 16, v135
	v_med3_f32 v3, v3, s14, v218
	v_mul_f32_e32 v139, 0xbfb8aa3b, v139
	v_mul_f32_e32 v3, 0xbfb8aa3b, v3
	v_exp_f32_e32 v138, v138
	v_exp_f32_e32 v139, v139
	v_exp_f32_e32 v3, v3
	v_lshl_add_u64 v[136:137], v[140:141], 0, v[190:191]
	v_pk_mul_f32 v[42:43], v[42:43], v[132:133]
	v_pk_add_f32 v[138:139], v[138:139], 1.0 op_sel_hi:[1,0]
	v_add_f32_e32 v3, 1.0, v3
	v_pk_mul_f32 v[138:139], v[138:139], v[142:143]
	v_lshlrev_b32_e32 v132, 16, v146
	v_and_b32_e32 v133, 0xffff0000, v146
	v_rcp_f32_e32 v146, v3
	v_and_b32_e32 v3, 0xffff0000, v135
	v_pk_mul_f32 v[54:55], v[54:55], v[138:139]
	flat_load_dwordx4 v[136:139], v[136:137]
	v_med3_f32 v3, v3, s14, v218
	v_mul_f32_e32 v3, 0xbfb8aa3b, v3
	v_exp_f32_e32 v3, v3
	v_lshlrev_b32_e32 v134, 16, v147
	v_and_b32_e32 v135, 0xffff0000, v147
	v_lshl_add_u64 v[140:141], v[140:141], 0, v[192:193]
	v_add_f32_e32 v3, 1.0, v3
	v_rcp_f32_e32 v147, v3
	v_lshlrev_b32_e32 v3, 16, v152
	v_med3_f32 v3, v3, s14, v218
	v_mul_f32_e32 v3, 0xbfb8aa3b, v3
	v_exp_f32_e32 v3, v3
	flat_load_dwordx4 v[140:143], v[140:141]
	v_lshlrev_b32_e32 v164, 16, v156
	v_add_f32_e32 v3, 1.0, v3
	v_rcp_f32_e32 v166, v3
	v_and_b32_e32 v3, 0xffff0000, v152
	v_med3_f32 v3, v3, s14, v218
	v_mul_f32_e32 v3, 0xbfb8aa3b, v3
	v_exp_f32_e32 v3, v3
	v_and_b32_e32 v152, 0xffff0000, v156
	v_med3_f32 v152, v152, s14, v218
	v_add_f32_e32 v3, 1.0, v3
	v_rcp_f32_e32 v167, v3
	v_lshlrev_b32_e32 v3, 16, v153
	v_med3_f32 v3, v3, s14, v218
	v_mul_f32_e32 v3, 0xbfb8aa3b, v3
	v_exp_f32_e32 v3, v3
	v_mul_f32_e32 v152, 0xbfb8aa3b, v152
	v_exp_f32_e32 v165, v152
	v_lshlrev_b32_e32 v152, 16, v157
	v_add_f32_e32 v3, 1.0, v3
	v_rcp_f32_e32 v156, v3
	v_and_b32_e32 v3, 0xffff0000, v153
	v_med3_f32 v3, v3, s14, v218
	v_mul_f32_e32 v3, 0xbfb8aa3b, v3
	v_exp_f32_e32 v3, v3
	v_and_b32_e32 v153, 0xffff0000, v157
	v_add_f32_e32 v3, 1.0, v3
	v_rcp_f32_e32 v157, v3
	v_lshlrev_b32_e32 v3, 16, v154
	v_med3_f32 v152, v152, s14, v218
	v_med3_f32 v153, v153, s14, v218
	v_med3_f32 v3, v3, s14, v218
	v_mul_f32_e32 v152, 0xbfb8aa3b, v152
	v_mul_f32_e32 v153, 0xbfb8aa3b, v153
	v_mul_f32_e32 v3, 0xbfb8aa3b, v3
	v_exp_f32_e32 v152, v152
	v_exp_f32_e32 v153, v153
	v_exp_f32_e32 v3, v3
	s_nop 0
	v_pk_add_f32 v[152:153], v[152:153], 1.0 op_sel_hi:[1,0]
	v_add_f32_e32 v3, 1.0, v3
	v_pk_mul_f32 v[152:153], v[152:153], v[156:157]
	v_rcp_f32_e32 v156, v3
	v_and_b32_e32 v3, 0xffff0000, v154
	v_med3_f32 v3, v3, s14, v218
	v_mul_f32_e32 v3, 0xbfb8aa3b, v3
	v_exp_f32_e32 v3, v3
	v_med3_f32 v132, v132, s14, v218
	v_med3_f32 v133, v133, s14, v218
	v_med3_f32 v148, v148, s14, v218
	v_add_f32_e32 v3, 1.0, v3
	v_rcp_f32_e32 v157, v3
	v_lshlrev_b32_e32 v3, 16, v155
	v_mul_f32_e32 v132, 0xbfb8aa3b, v132
	v_mul_f32_e32 v133, 0xbfb8aa3b, v133
	v_med3_f32 v3, v3, s14, v218
	v_mul_f32_e32 v148, 0xbfb8aa3b, v148
	v_exp_f32_e32 v132, v132
	v_exp_f32_e32 v133, v133
	v_mul_f32_e32 v3, 0xbfb8aa3b, v3
	v_exp_f32_e32 v148, v148
	v_exp_f32_e32 v3, v3
	v_pk_add_f32 v[132:133], v[132:133], 1.0 op_sel_hi:[1,0]
	s_mov_b64 s[46:47], 0xb000
	v_pk_add_f32 v[148:149], v[148:149], 1.0 op_sel_hi:[1,0]
	v_pk_mul_f32 v[132:133], v[132:133], v[144:145]
	v_lshl_add_u64 v[144:145], v[182:183], 0, s[46:47]
	v_add_f32_e32 v3, 1.0, v3
	v_pk_mul_f32 v[148:149], v[148:149], v[150:151]
	v_pk_mul_f32 v[36:37], v[36:37], v[132:133]
	v_lshl_add_u64 v[132:133], v[144:145], 0, v[186:187]
	v_pk_mul_f32 v[34:35], v[34:35], v[152:153]
	v_lshlrev_b32_e32 v152, 16, v158
	v_and_b32_e32 v153, 0xffff0000, v158
	v_rcp_f32_e32 v158, v3
	v_and_b32_e32 v3, 0xffff0000, v155
	v_pk_mul_f32 v[40:41], v[40:41], v[148:149]
	flat_load_dwordx4 v[148:151], v[132:133]
	v_med3_f32 v3, v3, s14, v218
	v_mul_f32_e32 v3, 0xbfb8aa3b, v3
	v_exp_f32_e32 v3, v3
	v_lshlrev_b32_e32 v154, 16, v159
	v_and_b32_e32 v155, 0xffff0000, v159
	v_add_f32_e32 v3, 1.0, v3
	v_rcp_f32_e32 v159, v3
	s_waitcnt vmcnt(0) lgkmcnt(0)
; __device__ __forceinline__ float bflo(unsigned u) { return __uint_as_float(u << 16); }
; __device__ __forceinline__ float bfhi(unsigned u) { return __uint_as_float(u & 0xffff0000u); }
; #define HOOK_LD(it, bf) do { const int gr = row0 + ((it) >> 2) * 128 + ((it) & 3) * 16; \
;         _Pragma("unroll") for (int bj = 0; bj < 2; ++bj) { gb[bf][bj][0] = *(const u32x4*)(P + pidx(gr, gc0 + bj * 128)); gb[bf][bj][1] = *(const u32x4*)(P + pidx(gr, gc0 + 2048 + bj * 128)); } } while (0)
; __device__ __forceinline__ float sigratio(float a, float b) { return (1.f + __expf(-fminf(fmaxf(b, -30.f), 30.f))) * __builtin_amdgcn_rcpf(1.f + __expf(-fminf(fmaxf(a, -30.f), 30.f))); }
;     __device__ __forceinline__ void hook(f32x4 (&acc)[2][2][4][2], const pg8::Unit& u, int wr, int wc, int fr, int fq, int which) const {
;     ...
;         HOOK_LD(0, 0);
; #pragma unroll
;         for (int it = 0; it < 8; ++it) {
;             if (it < 7) HOOK_LD(it + 1, (it + 1) & 1);
;             const int ai = it >> 2, m = it & 3;
; #pragma unroll
;             for (int bj = 0; bj < 2; ++bj) {
;                 const u32x4 ga = gb[it & 1][bj][0], gq = gb[it & 1][bj][1];
; #pragma unroll
;                 for (int n = 0; n < 2; ++n) {
;                     f32x4 r = {sigratio(bflo(ga[2 * n]), bflo(gq[2 * n])), sigratio(bfhi(ga[2 * n]), bfhi(gq[2 * n])), sigratio(bflo(ga[2 * n + 1]), bflo(gq[2 * n + 1])), sigratio(bfhi(ga[2 * n + 1]), bfhi(gq[2 * n + 1]))};
;                     acc[ai][bj][m][n] *= r;
;                 }
;             }
;             asm volatile("" ::: "memory");
	v_lshlrev_b32_e32 v3, 16, v136
	v_med3_f32 v154, v154, s14, v218
	v_med3_f32 v155, v155, s14, v218
	v_mul_f32_e32 v154, 0xbfb8aa3b, v154
	v_mul_f32_e32 v155, 0xbfb8aa3b, v155
	v_med3_f32 v3, v3, s14, v218
	v_exp_f32_e32 v154, v154
	v_exp_f32_e32 v155, v155
	v_mul_f32_e32 v3, 0xbfb8aa3b, v3
	v_exp_f32_e32 v3, v3
	s_nop 0
	v_pk_add_f32 v[154:155], v[154:155], 1.0 op_sel_hi:[1,0]
	v_pk_mul_f32 v[154:155], v[154:155], v[158:159]
	v_add_f32_e32 v3, 1.0, v3
	v_pk_mul_f32 v[30:31], v[30:31], v[154:155]
	v_rcp_f32_e32 v154, v3
	v_and_b32_e32 v3, 0xffff0000, v136
	v_med3_f32 v3, v3, s14, v218
	v_mul_f32_e32 v3, 0xbfb8aa3b, v3
	v_exp_f32_e32 v3, v3
	v_med3_f32 v152, v152, s14, v218
	v_med3_f32 v153, v153, s14, v218
	v_mul_f32_e32 v152, 0xbfb8aa3b, v152
	v_add_f32_e32 v3, 1.0, v3
	v_rcp_f32_e32 v155, v3
	v_lshlrev_b32_e32 v3, 16, v137
	v_mul_f32_e32 v153, 0xbfb8aa3b, v153
	v_med3_f32 v3, v3, s14, v218
	v_exp_f32_e32 v152, v152
	v_exp_f32_e32 v153, v153
	v_mul_f32_e32 v3, 0xbfb8aa3b, v3
	v_exp_f32_e32 v3, v3
	v_lshl_add_u64 v[132:133], v[144:145], 0, v[188:189]
	v_pk_add_f32 v[152:153], v[152:153], 1.0 op_sel_hi:[1,0]
	flat_load_dwordx4 v[160:163], v[132:133]
	v_pk_mul_f32 v[152:153], v[152:153], v[156:157]
	v_add_f32_e32 v3, 1.0, v3
	v_pk_mul_f32 v[28:29], v[28:29], v[152:153]
	v_lshlrev_b32_e32 v152, 16, v140
	v_and_b32_e32 v136, 0xffff0000, v140
	v_rcp_f32_e32 v140, v3
	v_and_b32_e32 v3, 0xffff0000, v137
	v_med3_f32 v3, v3, s14, v218
	v_mul_f32_e32 v3, 0xbfb8aa3b, v3
	v_exp_f32_e32 v3, v3
	s_nop 0
	v_med3_f32 v136, v136, s14, v218
	v_mul_f32_e32 v136, 0xbfb8aa3b, v136
	v_add_f32_e32 v3, 1.0, v3
	v_exp_f32_e32 v153, v136
	v_lshlrev_b32_e32 v136, 16, v141
	v_and_b32_e32 v137, 0xffff0000, v141
	v_rcp_f32_e32 v141, v3
	v_lshlrev_b32_e32 v3, 16, v138
	v_med3_f32 v136, v136, s14, v218
	v_med3_f32 v137, v137, s14, v218
	v_med3_f32 v3, v3, s14, v218
	v_mul_f32_e32 v136, 0xbfb8aa3b, v136
	v_mul_f32_e32 v137, 0xbfb8aa3b, v137
	v_mul_f32_e32 v3, 0xbfb8aa3b, v3
	v_exp_f32_e32 v136, v136
	v_exp_f32_e32 v137, v137
	v_exp_f32_e32 v3, v3
	s_nop 0
	v_pk_add_f32 v[136:137], v[136:137], 1.0 op_sel_hi:[1,0]
	v_add_f32_e32 v3, 1.0, v3
	v_pk_mul_f32 v[136:137], v[136:137], v[140:141]
	v_rcp_f32_e32 v140, v3
	v_and_b32_e32 v3, 0xffff0000, v138
	v_med3_f32 v3, v3, s14, v218
	v_mul_f32_e32 v3, 0xbfb8aa3b, v3
	v_exp_f32_e32 v3, v3
	v_med3_f32 v134, v134, s14, v218
	v_med3_f32 v135, v135, s14, v218
	v_mul_f32_e32 v134, 0xbfb8aa3b, v134
	v_add_f32_e32 v3, 1.0, v3
	v_rcp_f32_e32 v141, v3
	v_lshlrev_b32_e32 v3, 16, v139
	v_med3_f32 v3, v3, s14, v218
	v_mul_f32_e32 v135, 0xbfb8aa3b, v135
	v_mul_f32_e32 v3, 0xbfb8aa3b, v3
	v_exp_f32_e32 v134, v134
	v_exp_f32_e32 v135, v135
	v_exp_f32_e32 v3, v3
	v_lshl_add_u64 v[132:133], v[144:145], 0, v[190:191]
	v_pk_mul_f32 v[26:27], v[26:27], v[136:137]
	v_pk_add_f32 v[134:135], v[134:135], 1.0 op_sel_hi:[1,0]
	v_add_f32_e32 v3, 1.0, v3
	v_pk_mul_f32 v[134:135], v[134:135], v[146:147]
	v_lshlrev_b32_e32 v136, 16, v142
	v_and_b32_e32 v137, 0xffff0000, v142
	v_rcp_f32_e32 v142, v3
	v_and_b32_e32 v3, 0xffff0000, v139
	v_pk_mul_f32 v[38:39], v[38:39], v[134:135]
	flat_load_dwordx4 v[132:135], v[132:133]
	v_med3_f32 v3, v3, s14, v218
	v_mul_f32_e32 v3, 0xbfb8aa3b, v3
	v_exp_f32_e32 v3, v3
	v_lshlrev_b32_e32 v138, 16, v143
	v_and_b32_e32 v139, 0xffff0000, v143
	v_add_f32_e32 v3, 1.0, v3
	v_rcp_f32_e32 v143, v3
	v_lshlrev_b32_e32 v3, 16, v148
	v_med3_f32 v138, v138, s14, v218
	v_med3_f32 v139, v139, s14, v218
	v_mul_f32_e32 v138, 0xbfb8aa3b, v138
	v_mul_f32_e32 v139, 0xbfb8aa3b, v139
	v_med3_f32 v3, v3, s14, v218
	v_exp_f32_e32 v138, v138
	v_exp_f32_e32 v139, v139
	v_mul_f32_e32 v3, 0xbfb8aa3b, v3
	v_exp_f32_e32 v3, v3
	v_lshl_add_u64 v[144:145], v[144:145], 0, v[192:193]
	v_pk_add_f32 v[138:139], v[138:139], 1.0 op_sel_hi:[1,0]
	v_pk_mul_f32 v[138:139], v[138:139], v[142:143]
	v_add_f32_e32 v3, 1.0, v3
	v_pk_mul_f32 v[22:23], v[22:23], v[138:139]
	v_rcp_f32_e32 v138, v3
	v_and_b32_e32 v3, 0xffff0000, v148
	v_med3_f32 v3, v3, s14, v218
	v_mul_f32_e32 v3, 0xbfb8aa3b, v3
	v_exp_f32_e32 v3, v3
	s_nop 0
	flat_load_dwordx4 v[144:147], v[144:145]
	v_med3_f32 v136, v136, s14, v218
	v_add_f32_e32 v3, 1.0, v3
	v_rcp_f32_e32 v139, v3
	v_lshlrev_b32_e32 v3, 16, v149
	v_med3_f32 v3, v3, s14, v218
	v_mul_f32_e32 v3, 0xbfb8aa3b, v3
	v_exp_f32_e32 v3, v3
	v_med3_f32 v137, v137, s14, v218
	v_mul_f32_e32 v136, 0xbfb8aa3b, v136
	v_mul_f32_e32 v137, 0xbfb8aa3b, v137
	v_add_f32_e32 v3, 1.0, v3
	v_rcp_f32_e32 v142, v3
	v_and_b32_e32 v3, 0xffff0000, v149
	v_exp_f32_e32 v136, v136
	v_exp_f32_e32 v137, v137
	v_med3_f32 v3, v3, s14, v218
	v_mul_f32_e32 v3, 0xbfb8aa3b, v3
	v_exp_f32_e32 v3, v3
	v_pk_add_f32 v[136:137], v[136:137], 1.0 op_sel_hi:[1,0]
	v_pk_mul_f32 v[136:137], v[136:137], v[140:141]
	s_waitcnt vmcnt(0) lgkmcnt(0)
; __device__ __forceinline__ float bflo(unsigned u) { return __uint_as_float(u << 16); }
; __device__ __forceinline__ float bfhi(unsigned u) { return __uint_as_float(u & 0xffff0000u); }
; #define HOOK_LD(it, bf) do { const int gr = row0 + ((it) >> 2) * 128 + ((it) & 3) * 16; \
;         _Pragma("unroll") for (int bj = 0; bj < 2; ++bj) { gb[bf][bj][0] = *(const u32x4*)(P + pidx(gr, gc0 + bj * 128)); gb[bf][bj][1] = *(const u32x4*)(P + pidx(gr, gc0 + 2048 + bj * 128)); } } while (0)
; __device__ __forceinline__ float sigratio(float a, float b) { return (1.f + __expf(-fminf(fmaxf(b, -30.f), 30.f))) * __builtin_amdgcn_rcpf(1.f + __expf(-fminf(fmaxf(a, -30.f), 30.f))); }
;     __device__ __forceinline__ void hook(f32x4 (&acc)[2][2][4][2], const pg8::Unit& u, int wr, int wc, int fr, int fq, int which) const {
;     ...
;         HOOK_LD(0, 0);
; #pragma unroll
;         for (int it = 0; it < 8; ++it) {
;             if (it < 7) HOOK_LD(it + 1, (it + 1) & 1);
;             const int ai = it >> 2, m = it & 3;
; #pragma unroll
;             for (int bj = 0; bj < 2; ++bj) {
;                 const u32x4 ga = gb[it & 1][bj][0], gq = gb[it & 1][bj][1];
; #pragma unroll
;                 for (int n = 0; n < 2; ++n) {
;                     f32x4 r = {sigratio(bflo(ga[2 * n]), bflo(gq[2 * n])), sigratio(bfhi(ga[2 * n]), bfhi(gq[2 * n])), sigratio(bflo(ga[2 * n + 1]), bflo(gq[2 * n + 1])), sigratio(bfhi(ga[2 * n + 1]), bfhi(gq[2 * n + 1]))};
;                     acc[ai][bj][m][n] *= r;
;                 }
;             }
;             asm volatile("" ::: "memory");
	v_lshlrev_b32_e32 v140, 16, v161
	v_pk_mul_f32 v[20:21], v[20:21], v[136:137]
	v_lshlrev_b32_e32 v136, 16, v160
	v_and_b32_e32 v137, 0xffff0000, v160
	v_and_b32_e32 v141, 0xffff0000, v161
	v_add_f32_e32 v3, 1.0, v3
	v_rcp_f32_e32 v143, v3
	v_lshlrev_b32_e32 v3, 16, v150
	v_med3_f32 v136, v136, s14, v218
	v_med3_f32 v137, v137, s14, v218
	v_med3_f32 v140, v140, s14, v218
	v_med3_f32 v141, v141, s14, v218
	v_mul_f32_e32 v136, 0xbfb8aa3b, v136
	v_mul_f32_e32 v137, 0xbfb8aa3b, v137
	v_mul_f32_e32 v140, 0xbfb8aa3b, v140
	v_mul_f32_e32 v141, 0xbfb8aa3b, v141
	v_med3_f32 v3, v3, s14, v218
	v_exp_f32_e32 v136, v136
	v_exp_f32_e32 v137, v137
	v_exp_f32_e32 v140, v140
	v_exp_f32_e32 v141, v141
	v_mul_f32_e32 v3, 0xbfb8aa3b, v3
	v_exp_f32_e32 v3, v3
	v_pk_add_f32 v[136:137], v[136:137], 1.0 op_sel_hi:[1,0]
	v_pk_add_f32 v[140:141], v[140:141], 1.0 op_sel_hi:[1,0]
	v_pk_mul_f32 v[136:137], v[136:137], v[138:139]
	v_pk_mul_f32 v[138:139], v[140:141], v[142:143]
	v_add_f32_e32 v3, 1.0, v3
	v_pk_mul_f32 v[18:19], v[18:19], v[138:139]
	v_rcp_f32_e32 v138, v3
	v_and_b32_e32 v3, 0xffff0000, v150
	v_med3_f32 v3, v3, s14, v218
	v_mul_f32_e32 v3, 0xbfb8aa3b, v3
	v_exp_f32_e32 v3, v3
	v_pk_mul_f32 v[16:17], v[16:17], v[136:137]
	v_lshlrev_b32_e32 v136, 16, v162
	v_and_b32_e32 v137, 0xffff0000, v162
	v_add_f32_e32 v3, 1.0, v3
	v_rcp_f32_e32 v139, v3
	v_lshlrev_b32_e32 v3, 16, v151
	v_med3_f32 v3, v3, s14, v218
	v_mul_f32_e32 v3, 0xbfb8aa3b, v3
	v_exp_f32_e32 v3, v3
	v_lshlrev_b32_e32 v140, 16, v163
	v_and_b32_e32 v141, 0xffff0000, v163
	v_add_f32_e32 v3, 1.0, v3
	v_rcp_f32_e32 v142, v3
	v_and_b32_e32 v3, 0xffff0000, v151
	v_med3_f32 v3, v3, s14, v218
	v_mul_f32_e32 v3, 0xbfb8aa3b, v3
	v_exp_f32_e32 v3, v3
	s_nop 0
	v_add_f32_e32 v3, 1.0, v3
	v_rcp_f32_e32 v143, v3
	v_lshlrev_b32_e32 v3, 16, v132
	v_med3_f32 v136, v136, s14, v218
	v_med3_f32 v137, v137, s14, v218
	v_med3_f32 v140, v140, s14, v218
	v_med3_f32 v141, v141, s14, v218
	v_mul_f32_e32 v136, 0xbfb8aa3b, v136
	v_mul_f32_e32 v137, 0xbfb8aa3b, v137
	v_mul_f32_e32 v140, 0xbfb8aa3b, v140
	v_mul_f32_e32 v141, 0xbfb8aa3b, v141
	v_med3_f32 v3, v3, s14, v218
	v_exp_f32_e32 v136, v136
	v_exp_f32_e32 v137, v137
	v_exp_f32_e32 v140, v140
	v_exp_f32_e32 v141, v141
	v_mul_f32_e32 v3, 0xbfb8aa3b, v3
	v_exp_f32_e32 v3, v3
	v_pk_add_f32 v[136:137], v[136:137], 1.0 op_sel_hi:[1,0]
	v_pk_add_f32 v[140:141], v[140:141], 1.0 op_sel_hi:[1,0]
	v_pk_mul_f32 v[136:137], v[136:137], v[138:139]
	v_pk_mul_f32 v[138:139], v[140:141], v[142:143]
	v_add_f32_e32 v3, 1.0, v3
	v_pk_mul_f32 v[14:15], v[14:15], v[138:139]
	v_rcp_f32_e32 v138, v3
	v_and_b32_e32 v3, 0xffff0000, v132
	v_med3_f32 v3, v3, s14, v218
	v_mul_f32_e32 v3, 0xbfb8aa3b, v3
	v_exp_f32_e32 v3, v3
	v_pk_mul_f32 v[12:13], v[12:13], v[136:137]
	v_lshlrev_b32_e32 v136, 16, v144
	v_and_b32_e32 v132, 0xffff0000, v144
	v_add_f32_e32 v3, 1.0, v3
	v_rcp_f32_e32 v139, v3
	v_lshlrev_b32_e32 v3, 16, v133
	v_med3_f32 v3, v3, s14, v218
	v_mul_f32_e32 v3, 0xbfb8aa3b, v3
	v_exp_f32_e32 v3, v3
	s_nop 0
	v_med3_f32 v136, v136, s14, v218
	v_add_f32_e32 v3, 1.0, v3
	v_rcp_f32_e32 v140, v3
	v_and_b32_e32 v3, 0xffff0000, v133
	v_med3_f32 v3, v3, s14, v218
	v_mul_f32_e32 v3, 0xbfb8aa3b, v3
	v_exp_f32_e32 v3, v3
	v_med3_f32 v132, v132, s14, v218
	v_mul_f32_e32 v136, 0xbfb8aa3b, v136
	v_mul_f32_e32 v132, 0xbfb8aa3b, v132
	v_add_f32_e32 v3, 1.0, v3
	v_rcp_f32_e32 v141, v3
	v_lshlrev_b32_e32 v3, 16, v134
	v_med3_f32 v3, v3, s14, v218
	v_exp_f32_e32 v136, v136
	v_exp_f32_e32 v137, v132
	v_mul_f32_e32 v3, 0xbfb8aa3b, v3
	v_exp_f32_e32 v3, v3
	v_lshlrev_b32_e32 v132, 16, v145
	v_pk_add_f32 v[136:137], v[136:137], 1.0 op_sel_hi:[1,0]
	v_and_b32_e32 v133, 0xffff0000, v145
	v_pk_mul_f32 v[136:137], v[136:137], v[138:139]
	v_add_f32_e32 v3, 1.0, v3
	v_pk_mul_f32 v[8:9], v[8:9], v[136:137]
	v_rcp_f32_e32 v136, v3
	v_and_b32_e32 v3, 0xffff0000, v134
	v_med3_f32 v3, v3, s14, v218
	v_mul_f32_e32 v3, 0xbfb8aa3b, v3
	v_exp_f32_e32 v3, v3
	s_nop 0
	v_med3_f32 v132, v132, s14, v218
	v_add_f32_e32 v3, 1.0, v3
	v_rcp_f32_e32 v137, v3
	v_lshlrev_b32_e32 v3, 16, v135
	v_med3_f32 v3, v3, s14, v218
	v_mul_f32_e32 v3, 0xbfb8aa3b, v3
	v_exp_f32_e32 v3, v3
	v_med3_f32 v133, v133, s14, v218
	v_mul_f32_e32 v132, 0xbfb8aa3b, v132
	v_mul_f32_e32 v133, 0xbfb8aa3b, v133
	v_exp_f32_e32 v132, v132
	v_exp_f32_e32 v133, v133
	v_add_f32_e32 v3, 1.0, v3
	v_rcp_f32_e32 v138, v3
	v_and_b32_e32 v3, 0xffff0000, v135
	v_pk_add_f32 v[132:133], v[132:133], 1.0 op_sel_hi:[1,0]
	v_med3_f32 v3, v3, s14, v218
	v_pk_mul_f32 v[132:133], v[132:133], v[140:141]
	v_mul_f32_e32 v3, 0xbfb8aa3b, v3
	v_pk_mul_f32 v[10:11], v[10:11], v[132:133]
	v_lshlrev_b32_e32 v132, 16, v146
	v_and_b32_e32 v133, 0xffff0000, v146
	v_lshlrev_b32_e32 v134, 16, v147
	v_and_b32_e32 v135, 0xffff0000, v147
	v_exp_f32_e32 v3, v3
	s_nop 0
	v_med3_f32 v164, v164, s14, v218
	v_med3_f32 v152, v152, s14, v218
	v_med3_f32 v132, v132, s14, v218
	v_med3_f32 v133, v133, s14, v218
	v_med3_f32 v134, v134, s14, v218
	v_med3_f32 v135, v135, s14, v218
	v_mul_f32_e32 v164, 0xbfb8aa3b, v164
	v_mul_f32_e32 v152, 0xbfb8aa3b, v152
	v_mul_f32_e32 v132, 0xbfb8aa3b, v132
	v_mul_f32_e32 v133, 0xbfb8aa3b, v133
	v_mul_f32_e32 v134, 0xbfb8aa3b, v134
	v_mul_f32_e32 v135, 0xbfb8aa3b, v135
	v_exp_f32_e32 v164, v164
	v_exp_f32_e32 v152, v152
	v_exp_f32_e32 v132, v132
	v_exp_f32_e32 v133, v133
	v_exp_f32_e32 v134, v134
	v_exp_f32_e32 v135, v135
	v_add_f32_e32 v3, 1.0, v3
	v_rcp_f32_e32 v139, v3
	v_pk_add_f32 v[164:165], v[164:165], 1.0 op_sel_hi:[1,0]
	v_pk_add_f32 v[152:153], v[152:153], 1.0 op_sel_hi:[1,0]
	v_pk_add_f32 v[134:135], v[134:135], 1.0 op_sel_hi:[1,0]
	v_pk_add_f32 v[132:133], v[132:133], 1.0 op_sel_hi:[1,0]
	v_pk_mul_f32 v[164:165], v[164:165], v[166:167]
	v_pk_mul_f32 v[152:153], v[152:153], v[154:155]
	v_pk_mul_f32 v[132:133], v[132:133], v[136:137]
	v_pk_mul_f32 v[134:135], v[134:135], v[138:139]
	v_pk_mul_f32 v[32:33], v[32:33], v[164:165]
	v_pk_mul_f32 v[24:25], v[24:25], v[152:153]
	v_pk_mul_f32 v[6:7], v[6:7], v[134:135]
	v_pk_mul_f32 v[4:5], v[4:5], v[132:133]
	s_branch .LBB0_203

; __device__ __forceinline__ unsigned pk2(float lo, float hi) { const f32v2_t v = {lo, hi}; return __builtin_bit_cast(unsigned, __builtin_convertvector(v, bf16v2_t)); }
; __device__ __forceinline__ float bflo(unsigned u) { return __uint_as_float(u << 16); }
; __device__ __forceinline__ float bfhi(unsigned u) { return __uint_as_float(u & 0xffff0000u); }
; __device__ __forceinline__ float sigc(float x) { return __builtin_amdgcn_rcpf(1.f + __expf(-fminf(fmaxf(x, -30.f), 30.f))); }
; #define M1_LD(it, bf) do { const int gr = row0 + ((it) >> 2) * 128 + ((it) & 3) * 16; \
;             _Pragma("unroll") for (int bj = 0; bj < 2; ++bj) gb[bf][bj] = *(const u32x4*)(P + pidx(gr, gc2 + bj * 128)); } while (0)
;     __device__ __forceinline__ void operator()(const f32x4 (&acc)[2][2][4][2], const pg8::Unit& u, int wr, int wc, int fr, int fq) const {
;     ...
;         } else if (mode == 1) {
;             bf16_t* const YB = (bf16_t*)(ws + W_YB);
;             const int col0 = u.pn * 256 + wc * 32 + 8 * fq;
;             const int gc2 = C_GATE + 4096 + col0;
;             u32x4 gb[2][2];
;     ...
;             M1_LD(0, 0);
; #pragma unroll
;             for (int it = 0; it < 8; ++it) {
;                 if (it < 7) M1_LD(it + 1, (it + 1) & 1);
;                 const int ai = it >> 2, m = it & 3, row = row0 + ai * 128 + m * 16;
; #pragma unroll
;                 for (int bj = 0; bj < 2; ++bj) {
;                     const u32x4 gw = gb[it & 1][bj];
;                     const f32x4 a0 = acc[ai][bj][m][0], a1 = acc[ai][bj][m][1];
;                     u32x4 o = {pk2(sigc(bflo(gw[0])) * a0[0], sigc(bfhi(gw[0])) * a0[1]), pk2(sigc(bflo(gw[1])) * a0[2], sigc(bfhi(gw[1])) * a0[3]),
;                                pk2(sigc(bflo(gw[2])) * a1[0], sigc(bfhi(gw[2])) * a1[1]), pk2(sigc(bflo(gw[3])) * a1[2], sigc(bfhi(gw[3])) * a1[3])};
;                     *(u32x4*)(YB + (size_t)row * D + col0 + bj * 128) = o;
;                 }
.LBB0_219:
	s_and_b64 vcc, exec, s[92:93]
	s_cbranch_vccz .LBB0_226
	s_cmp_gt_i32 s25, 0
	s_mov_b64 s[92:93], -1
	s_cbranch_scc0 .LBB0_224
	s_cmp_eq_u32 s25, 1
	s_mov_b64 s[74:75], -1
	s_cbranch_scc0 .LBB0_223
	v_or_b32_e32 v132, s4, v198
	v_add_u32_e32 v133, 0x2e10, v132
	v_ashrrev_i32_e32 v3, 31, v2
	v_and_b32_e32 v0, 0x78, v133
	v_lshlrev_b64 v[134:135], 8, v[2:3]
	v_ashrrev_i32_e32 v136, 7, v133
	v_lshl_add_u64 v[134:135], s[80:81], 0, v[134:135]
	v_lshlrev_b32_e32 v0, 1, v0
	v_ashrrev_i32_e32 v137, 31, v136
	v_lshl_add_u64 v[134:135], v[134:135], 0, v[0:1]
	v_lshlrev_b64 v[154:155], 21, v[136:137]
	v_lshl_add_u64 v[136:137], v[134:135], 0, v[154:155]
	flat_load_dwordx4 v[144:147], v[136:137]
	v_add_u32_e32 v133, 0x2e90, v132
	v_ashrrev_i32_e32 v136, 7, v133
	v_ashrrev_i32_e32 v137, 31, v136
	v_lshlrev_b64 v[156:157], 21, v[136:137]
	v_lshl_add_u64 v[134:135], v[134:135], 0, v[156:157]
	flat_load_dwordx4 v[140:143], v[134:135]
	v_lshl_add_u64 v[158:159], s[80:81], 0, v[0:1]
	v_readlane_b32 s2, v245, 43
	v_add_u32_e32 v148, 16, v2
	v_ashrrev_i32_e32 v133, 31, v132
	v_readlane_b32 s3, v245, 44
	v_ashrrev_i32_e32 v149, 31, v148
	v_lshlrev_b64 v[150:151], 12, v[2:3]
	v_lshl_add_u64 v[152:153], v[132:133], 1, s[2:3]
	v_lshlrev_b64 v[132:133], 8, v[148:149]
	v_lshl_add_u64 v[132:133], v[158:159], 0, v[132:133]
	v_lshl_add_u64 v[134:135], v[132:133], 0, v[154:155]
	flat_load_dwordx4 v[136:139], v[134:135]
	v_lshl_add_u64 v[132:133], v[132:133], 0, v[156:157]
	v_lshl_add_u64 v[150:151], v[152:153], 0, v[150:151]
	flat_load_dwordx4 v[132:135], v[132:133]
	v_lshlrev_b64 v[148:149], 12, v[148:149]
	v_lshl_add_u64 v[148:149], v[152:153], 0, v[148:149]
	v_add_u32_e32 v162, 48, v2
	v_ashrrev_i32_e32 v163, 31, v162
	s_mov_b64 s[74:75], 0
	s_waitcnt vmcnt(0) lgkmcnt(0)
	v_lshlrev_b32_e32 v0, 16, v144
	v_med3_f32 v0, v0, s14, v218
	v_mul_f32_e32 v0, 0xbfb8aa3b, v0
	v_exp_f32_e32 v0, v0
	s_nop 0
	v_add_f32_e32 v0, 1.0, v0
	v_rcp_f32_e32 v160, v0
	v_and_b32_e32 v0, 0xffff0000, v144
	v_med3_f32 v0, v0, s14, v218
	v_mul_f32_e32 v0, 0xbfb8aa3b, v0
	v_exp_f32_e32 v0, v0
	s_nop 0
	v_add_f32_e32 v0, 1.0, v0
	v_rcp_f32_e32 v161, v0
	v_lshlrev_b32_e32 v0, 16, v145
	v_med3_f32 v0, v0, s14, v218
	v_mul_f32_e32 v0, 0xbfb8aa3b, v0
	v_exp_f32_e32 v0, v0
	v_pk_mul_f32 v[160:161], v[128:129], v[160:161]
	v_add_f32_e32 v0, 1.0, v0
	v_cvt_pk_bf16_f32 v144, v160, v161
	v_rcp_f32_e32 v160, v0
	v_and_b32_e32 v0, 0xffff0000, v145
	v_med3_f32 v0, v0, s14, v218
	v_mul_f32_e32 v0, 0xbfb8aa3b, v0
	v_exp_f32_e32 v0, v0
	s_nop 0
	v_add_f32_e32 v0, 1.0, v0
	v_rcp_f32_e32 v161, v0
	v_lshlrev_b32_e32 v0, 16, v146
	v_med3_f32 v0, v0, s14, v218
	v_mul_f32_e32 v0, 0xbfb8aa3b, v0
	v_exp_f32_e32 v0, v0
	v_pk_mul_f32 v[160:161], v[130:131], v[160:161]
	v_add_f32_e32 v0, 1.0, v0
	v_cvt_pk_bf16_f32 v145, v160, v161
	v_rcp_f32_e32 v160, v0
	v_and_b32_e32 v0, 0xffff0000, v146
	v_med3_f32 v0, v0, s14, v218
	v_mul_f32_e32 v0, 0xbfb8aa3b, v0
	v_exp_f32_e32 v0, v0
	s_nop 0
	v_add_f32_e32 v0, 1.0, v0
	v_rcp_f32_e32 v161, v0
	v_lshlrev_b32_e32 v0, 16, v147
	v_med3_f32 v0, v0, s14, v218
	v_mul_f32_e32 v0, 0xbfb8aa3b, v0
	v_exp_f32_e32 v0, v0
	v_pk_mul_f32 v[160:161], v[124:125], v[160:161]
	v_add_f32_e32 v0, 1.0, v0
	v_cvt_pk_bf16_f32 v146, v160, v161
	v_rcp_f32_e32 v160, v0
	v_and_b32_e32 v0, 0xffff0000, v147
	v_med3_f32 v0, v0, s14, v218
	v_mul_f32_e32 v0, 0xbfb8aa3b, v0
	v_exp_f32_e32 v0, v0
	s_nop 0
	v_add_f32_e32 v0, 1.0, v0
	v_rcp_f32_e32 v161, v0
	v_lshlrev_b32_e32 v0, 16, v140
	v_med3_f32 v0, v0, s14, v218
	v_mul_f32_e32 v0, 0xbfb8aa3b, v0
	v_exp_f32_e32 v0, v0
	v_pk_mul_f32 v[160:161], v[126:127], v[160:161]
	v_add_f32_e32 v0, 1.0, v0
	v_cvt_pk_bf16_f32 v147, v160, v161
	flat_store_dwordx4 v[150:151], v[144:147]
	v_add_u32_e32 v160, 32, v2
	v_ashrrev_i32_e32 v161, 31, v160
	v_rcp_f32_e32 v144, v0
	v_and_b32_e32 v0, 0xffff0000, v140
	v_med3_f32 v0, v0, s14, v218
	v_mul_f32_e32 v0, 0xbfb8aa3b, v0
	v_exp_f32_e32 v0, v0
	s_nop 0
	v_add_f32_e32 v0, 1.0, v0
	v_rcp_f32_e32 v145, v0
	v_lshlrev_b32_e32 v0, 16, v141
	v_med3_f32 v0, v0, s14, v218
	v_mul_f32_e32 v0, 0xbfb8aa3b, v0
	v_exp_f32_e32 v0, v0
	v_pk_mul_f32 v[144:145], v[120:121], v[144:145]
	v_add_f32_e32 v0, 1.0, v0
	v_cvt_pk_bf16_f32 v140, v144, v145
	v_rcp_f32_e32 v144, v0
	v_and_b32_e32 v0, 0xffff0000, v141
	v_med3_f32 v0, v0, s14, v218
	v_mul_f32_e32 v0, 0xbfb8aa3b, v0
	v_exp_f32_e32 v0, v0
	s_nop 0
	v_add_f32_e32 v0, 1.0, v0
	v_rcp_f32_e32 v145, v0
	v_lshlrev_b32_e32 v0, 16, v142
	v_med3_f32 v0, v0, s14, v218
	v_mul_f32_e32 v0, 0xbfb8aa3b, v0
	v_exp_f32_e32 v0, v0
	v_pk_mul_f32 v[144:145], v[122:123], v[144:145]
	v_add_f32_e32 v0, 1.0, v0
	v_cvt_pk_bf16_f32 v141, v144, v145
	v_rcp_f32_e32 v144, v0
	v_and_b32_e32 v0, 0xffff0000, v142
	v_med3_f32 v0, v0, s14, v218
	v_mul_f32_e32 v0, 0xbfb8aa3b, v0
	v_exp_f32_e32 v0, v0
	s_nop 0
	v_add_f32_e32 v0, 1.0, v0
	v_rcp_f32_e32 v145, v0
	v_lshlrev_b32_e32 v0, 16, v143
	v_med3_f32 v0, v0, s14, v218
	v_mul_f32_e32 v0, 0xbfb8aa3b, v0
	v_exp_f32_e32 v0, v0
	v_pk_mul_f32 v[144:145], v[116:117], v[144:145]
	v_add_f32_e32 v0, 1.0, v0
	v_cvt_pk_bf16_f32 v142, v144, v145
	v_rcp_f32_e32 v144, v0
	v_and_b32_e32 v0, 0xffff0000, v143
	v_med3_f32 v0, v0, s14, v218
	v_mul_f32_e32 v0, 0xbfb8aa3b, v0
	v_exp_f32_e32 v0, v0
	s_nop 0
	v_add_f32_e32 v0, 1.0, v0
	v_rcp_f32_e32 v145, v0
	v_lshlrev_b32_e32 v0, 16, v136
	v_med3_f32 v0, v0, s14, v218
	v_mul_f32_e32 v0, 0xbfb8aa3b, v0
	v_exp_f32_e32 v0, v0
	v_pk_mul_f32 v[144:145], v[118:119], v[144:145]
	v_add_f32_e32 v0, 1.0, v0
	v_cvt_pk_bf16_f32 v143, v144, v145
	flat_store_dwordx4 v[150:151], v[140:143] offset:256
	v_rcp_f32_e32 v150, v0
	v_and_b32_e32 v0, 0xffff0000, v136
; __device__ __forceinline__ unsigned pk2(float lo, float hi) { const f32v2_t v = {lo, hi}; return __builtin_bit_cast(unsigned, __builtin_convertvector(v, bf16v2_t)); }
; __device__ __forceinline__ float bflo(unsigned u) { return __uint_as_float(u << 16); }
; __device__ __forceinline__ float bfhi(unsigned u) { return __uint_as_float(u & 0xffff0000u); }
; #define M1_LD(it, bf) do { const int gr = row0 + ((it) >> 2) * 128 + ((it) & 3) * 16; \
;             _Pragma("unroll") for (int bj = 0; bj < 2; ++bj) gb[bf][bj] = *(const u32x4*)(P + pidx(gr, gc2 + bj * 128)); } while (0)
; __device__ __forceinline__ float sigc(float x) { return __builtin_amdgcn_rcpf(1.f + __expf(-fminf(fmaxf(x, -30.f), 30.f))); }
;     __device__ __forceinline__ void operator()(const f32x4 (&acc)[2][2][4][2], const pg8::Unit& u, int wr, int wc, int fr, int fq) const {
;     ...
;             M1_LD(0, 0);
; #pragma unroll
;             for (int it = 0; it < 8; ++it) {
;                 if (it < 7) M1_LD(it + 1, (it + 1) & 1);
;                 const int ai = it >> 2, m = it & 3, row = row0 + ai * 128 + m * 16;
; #pragma unroll
;                 for (int bj = 0; bj < 2; ++bj) {
;                     const u32x4 gw = gb[it & 1][bj];
;                     const f32x4 a0 = acc[ai][bj][m][0], a1 = acc[ai][bj][m][1];
;                     u32x4 o = {pk2(sigc(bflo(gw[0])) * a0[0], sigc(bfhi(gw[0])) * a0[1]), pk2(sigc(bflo(gw[1])) * a0[2], sigc(bfhi(gw[1])) * a0[3]),
;                                pk2(sigc(bflo(gw[2])) * a1[0], sigc(bfhi(gw[2])) * a1[1]), pk2(sigc(bflo(gw[3])) * a1[2], sigc(bfhi(gw[3])) * a1[3])};
;                     *(u32x4*)(YB + (size_t)row * D + col0 + bj * 128) = o;
;                 }
;                 asm volatile("" ::: "memory");
;             }
	v_med3_f32 v0, v0, s14, v218
	v_mul_f32_e32 v0, 0xbfb8aa3b, v0
	v_exp_f32_e32 v0, v0
	v_lshlrev_b64 v[140:141], 8, v[160:161]
	v_lshl_add_u64 v[140:141], v[158:159], 0, v[140:141]
	v_add_f32_e32 v0, 1.0, v0
	v_rcp_f32_e32 v151, v0
	v_lshlrev_b32_e32 v0, 16, v137
	v_med3_f32 v0, v0, s14, v218
	v_mul_f32_e32 v0, 0xbfb8aa3b, v0
	v_exp_f32_e32 v0, v0
	v_pk_mul_f32 v[150:151], v[112:113], v[150:151]
	v_lshl_add_u64 v[142:143], v[140:141], 0, v[154:155]
	v_cvt_pk_bf16_f32 v136, v150, v151
	v_add_f32_e32 v0, 1.0, v0
	v_rcp_f32_e32 v150, v0
	v_and_b32_e32 v0, 0xffff0000, v137
	v_med3_f32 v0, v0, s14, v218
	v_mul_f32_e32 v0, 0xbfb8aa3b, v0
	v_exp_f32_e32 v0, v0
	flat_load_dwordx4 v[144:147], v[142:143]
	v_lshl_add_u64 v[140:141], v[140:141], 0, v[156:157]
	flat_load_dwordx4 v[140:143], v[140:141]
	v_add_f32_e32 v0, 1.0, v0
	v_rcp_f32_e32 v151, v0
	v_lshlrev_b32_e32 v0, 16, v138
	v_med3_f32 v0, v0, s14, v218
	v_mul_f32_e32 v0, 0xbfb8aa3b, v0
	v_exp_f32_e32 v0, v0
	v_pk_mul_f32 v[150:151], v[114:115], v[150:151]
	v_add_f32_e32 v0, 1.0, v0
	v_cvt_pk_bf16_f32 v137, v150, v151
	v_rcp_f32_e32 v150, v0
	v_and_b32_e32 v0, 0xffff0000, v138
	v_med3_f32 v0, v0, s14, v218
	v_mul_f32_e32 v0, 0xbfb8aa3b, v0
	v_exp_f32_e32 v0, v0
	s_nop 0
	v_add_f32_e32 v0, 1.0, v0
	v_rcp_f32_e32 v151, v0
	v_lshlrev_b32_e32 v0, 16, v139
	v_med3_f32 v0, v0, s14, v218
	v_mul_f32_e32 v0, 0xbfb8aa3b, v0
	v_exp_f32_e32 v0, v0
	v_pk_mul_f32 v[150:151], v[108:109], v[150:151]
	v_add_f32_e32 v0, 1.0, v0
	v_cvt_pk_bf16_f32 v138, v150, v151
	v_rcp_f32_e32 v150, v0
	v_and_b32_e32 v0, 0xffff0000, v139
	v_med3_f32 v0, v0, s14, v218
	v_mul_f32_e32 v0, 0xbfb8aa3b, v0
	v_exp_f32_e32 v0, v0
	s_nop 0
	v_add_f32_e32 v0, 1.0, v0
	v_rcp_f32_e32 v151, v0
	v_lshlrev_b32_e32 v0, 16, v132
	v_med3_f32 v0, v0, s14, v218
	v_mul_f32_e32 v0, 0xbfb8aa3b, v0
	v_exp_f32_e32 v0, v0
	v_pk_mul_f32 v[150:151], v[110:111], v[150:151]
	v_add_f32_e32 v0, 1.0, v0
	v_cvt_pk_bf16_f32 v139, v150, v151
	flat_store_dwordx4 v[148:149], v[136:139]
	s_nop 1
	v_rcp_f32_e32 v136, v0
	v_and_b32_e32 v0, 0xffff0000, v132
	v_med3_f32 v0, v0, s14, v218
	v_mul_f32_e32 v0, 0xbfb8aa3b, v0
	v_exp_f32_e32 v0, v0
	s_nop 0
	v_add_f32_e32 v0, 1.0, v0
	v_rcp_f32_e32 v137, v0
	v_lshlrev_b32_e32 v0, 16, v133
	v_med3_f32 v0, v0, s14, v218
	v_mul_f32_e32 v0, 0xbfb8aa3b, v0
	v_exp_f32_e32 v0, v0
	v_pk_mul_f32 v[136:137], v[104:105], v[136:137]
	v_add_f32_e32 v0, 1.0, v0
	v_cvt_pk_bf16_f32 v132, v136, v137
	v_rcp_f32_e32 v136, v0
	v_and_b32_e32 v0, 0xffff0000, v133
	v_med3_f32 v0, v0, s14, v218
	v_mul_f32_e32 v0, 0xbfb8aa3b, v0
	v_exp_f32_e32 v0, v0
	s_nop 0
	v_add_f32_e32 v0, 1.0, v0
	v_rcp_f32_e32 v137, v0
	v_lshlrev_b32_e32 v0, 16, v134
	v_med3_f32 v0, v0, s14, v218
	v_mul_f32_e32 v0, 0xbfb8aa3b, v0
	v_exp_f32_e32 v0, v0
	v_pk_mul_f32 v[136:137], v[106:107], v[136:137]
	v_add_f32_e32 v0, 1.0, v0
	v_cvt_pk_bf16_f32 v133, v136, v137
	v_rcp_f32_e32 v136, v0
	v_and_b32_e32 v0, 0xffff0000, v134
	v_med3_f32 v0, v0, s14, v218
	v_mul_f32_e32 v0, 0xbfb8aa3b, v0
	v_exp_f32_e32 v0, v0
	s_nop 0
	v_add_f32_e32 v0, 1.0, v0
	v_rcp_f32_e32 v137, v0
	v_lshlrev_b32_e32 v0, 16, v135
	v_med3_f32 v0, v0, s14, v218
	v_mul_f32_e32 v0, 0xbfb8aa3b, v0
	v_exp_f32_e32 v0, v0
	v_pk_mul_f32 v[136:137], v[100:101], v[136:137]
	v_add_f32_e32 v0, 1.0, v0
	v_cvt_pk_bf16_f32 v134, v136, v137
	v_rcp_f32_e32 v136, v0
	v_and_b32_e32 v0, 0xffff0000, v135
	v_med3_f32 v0, v0, s14, v218
	v_mul_f32_e32 v0, 0xbfb8aa3b, v0
	v_exp_f32_e32 v0, v0
	s_nop 0
	v_add_f32_e32 v0, 1.0, v0
	v_rcp_f32_e32 v137, v0
	s_waitcnt vmcnt(0) lgkmcnt(0)
	v_lshlrev_b32_e32 v0, 16, v144
	v_med3_f32 v0, v0, s14, v218
	v_mul_f32_e32 v0, 0xbfb8aa3b, v0
	v_exp_f32_e32 v0, v0
	v_pk_mul_f32 v[136:137], v[102:103], v[136:137]
	v_add_f32_e32 v0, 1.0, v0
	v_rcp_f32_e32 v138, v0
	v_and_b32_e32 v0, 0xffff0000, v144
	v_med3_f32 v0, v0, s14, v218
	v_mul_f32_e32 v0, 0xbfb8aa3b, v0
	v_exp_f32_e32 v0, v0
	v_cvt_pk_bf16_f32 v135, v136, v137
	flat_store_dwordx4 v[148:149], v[132:135] offset:256
	v_add_f32_e32 v0, 1.0, v0
	v_rcp_f32_e32 v139, v0
	v_lshlrev_b32_e32 v0, 16, v145
	v_med3_f32 v0, v0, s14, v218
	v_mul_f32_e32 v0, 0xbfb8aa3b, v0
	v_exp_f32_e32 v0, v0
	v_pk_mul_f32 v[138:139], v[96:97], v[138:139]
	v_lshlrev_b64 v[132:133], 8, v[162:163]
	v_cvt_pk_bf16_f32 v144, v138, v139
	v_add_f32_e32 v0, 1.0, v0
	v_rcp_f32_e32 v138, v0
	v_and_b32_e32 v0, 0xffff0000, v145
	v_med3_f32 v0, v0, s14, v218
	v_mul_f32_e32 v0, 0xbfb8aa3b, v0
	v_exp_f32_e32 v0, v0
	v_lshl_add_u64 v[132:133], v[158:159], 0, v[132:133]
	v_lshl_add_u64 v[134:135], v[132:133], 0, v[154:155]
	flat_load_dwordx4 v[148:151], v[134:135]
	v_add_f32_e32 v0, 1.0, v0
	v_rcp_f32_e32 v139, v0
	v_lshlrev_b32_e32 v0, 16, v146
	v_med3_f32 v0, v0, s14, v218
	v_mul_f32_e32 v0, 0xbfb8aa3b, v0
	v_exp_f32_e32 v0, v0
	v_pk_mul_f32 v[138:139], v[98:99], v[138:139]
	v_lshl_add_u64 v[132:133], v[132:133], 0, v[156:157]
	v_cvt_pk_bf16_f32 v145, v138, v139
	v_add_f32_e32 v0, 1.0, v0
	v_rcp_f32_e32 v138, v0
	v_and_b32_e32 v0, 0xffff0000, v146
	v_med3_f32 v0, v0, s14, v218
	v_mul_f32_e32 v0, 0xbfb8aa3b, v0
	v_exp_f32_e32 v0, v0
	flat_load_dwordx4 v[132:135], v[132:133]
	v_lshlrev_b64 v[136:137], 12, v[160:161]
	v_lshl_add_u64 v[136:137], v[152:153], 0, v[136:137]
	v_add_f32_e32 v0, 1.0, v0
	v_rcp_f32_e32 v139, v0
	v_lshlrev_b32_e32 v0, 16, v147
	v_med3_f32 v0, v0, s14, v218
	v_mul_f32_e32 v0, 0xbfb8aa3b, v0
	v_exp_f32_e32 v0, v0
	v_pk_mul_f32 v[138:139], v[92:93], v[138:139]
	v_add_u32_e32 v160, 0x80, v2
	v_cvt_pk_bf16_f32 v146, v138, v139
	v_add_f32_e32 v0, 1.0, v0
	v_rcp_f32_e32 v138, v0
	v_and_b32_e32 v0, 0xffff0000, v147
	v_med3_f32 v0, v0, s14, v218
	v_mul_f32_e32 v0, 0xbfb8aa3b, v0
; __device__ __forceinline__ unsigned pk2(float lo, float hi) { const f32v2_t v = {lo, hi}; return __builtin_bit_cast(unsigned, __builtin_convertvector(v, bf16v2_t)); }
; __device__ __forceinline__ float bflo(unsigned u) { return __uint_as_float(u << 16); }
; __device__ __forceinline__ float bfhi(unsigned u) { return __uint_as_float(u & 0xffff0000u); }
; #define M1_LD(it, bf) do { const int gr = row0 + ((it) >> 2) * 128 + ((it) & 3) * 16; \
;             _Pragma("unroll") for (int bj = 0; bj < 2; ++bj) gb[bf][bj] = *(const u32x4*)(P + pidx(gr, gc2 + bj * 128)); } while (0)
; __device__ __forceinline__ float sigc(float x) { return __builtin_amdgcn_rcpf(1.f + __expf(-fminf(fmaxf(x, -30.f), 30.f))); }
;     __device__ __forceinline__ void operator()(const f32x4 (&acc)[2][2][4][2], const pg8::Unit& u, int wr, int wc, int fr, int fq) const {
;     ...
;             M1_LD(0, 0);
; #pragma unroll
;             for (int it = 0; it < 8; ++it) {
;                 if (it < 7) M1_LD(it + 1, (it + 1) & 1);
;                 const int ai = it >> 2, m = it & 3, row = row0 + ai * 128 + m * 16;
; #pragma unroll
;                 for (int bj = 0; bj < 2; ++bj) {
;                     const u32x4 gw = gb[it & 1][bj];
;                     const f32x4 a0 = acc[ai][bj][m][0], a1 = acc[ai][bj][m][1];
;                     u32x4 o = {pk2(sigc(bflo(gw[0])) * a0[0], sigc(bfhi(gw[0])) * a0[1]), pk2(sigc(bflo(gw[1])) * a0[2], sigc(bfhi(gw[1])) * a0[3]),
;                                pk2(sigc(bflo(gw[2])) * a1[0], sigc(bfhi(gw[2])) * a1[1]), pk2(sigc(bflo(gw[3])) * a1[2], sigc(bfhi(gw[3])) * a1[3])};
;                     *(u32x4*)(YB + (size_t)row * D + col0 + bj * 128) = o;
;                 }
;                 asm volatile("" ::: "memory");
;             }
	v_exp_f32_e32 v0, v0
	v_ashrrev_i32_e32 v161, 31, v160
	v_add_f32_e32 v0, 1.0, v0
	v_rcp_f32_e32 v139, v0
	v_lshlrev_b32_e32 v0, 16, v140
	v_med3_f32 v0, v0, s14, v218
	v_mul_f32_e32 v0, 0xbfb8aa3b, v0
	v_exp_f32_e32 v0, v0
	v_pk_mul_f32 v[138:139], v[94:95], v[138:139]
	v_add_f32_e32 v0, 1.0, v0
	v_cvt_pk_bf16_f32 v147, v138, v139
	v_rcp_f32_e32 v138, v0
	v_and_b32_e32 v0, 0xffff0000, v140
	v_med3_f32 v0, v0, s14, v218
	v_mul_f32_e32 v0, 0xbfb8aa3b, v0
	v_exp_f32_e32 v0, v0
	flat_store_dwordx4 v[136:137], v[144:147]
	v_add_f32_e32 v0, 1.0, v0
	v_rcp_f32_e32 v139, v0
	v_lshlrev_b32_e32 v0, 16, v141
	v_med3_f32 v0, v0, s14, v218
	v_mul_f32_e32 v0, 0xbfb8aa3b, v0
	v_exp_f32_e32 v0, v0
	v_pk_mul_f32 v[138:139], v[88:89], v[138:139]
	v_lshlrev_b64 v[144:145], 12, v[162:163]
	v_cvt_pk_bf16_f32 v138, v138, v139
	v_add_f32_e32 v0, 1.0, v0
	v_rcp_f32_e32 v140, v0
	v_and_b32_e32 v0, 0xffff0000, v141
	v_med3_f32 v0, v0, s14, v218
	v_mul_f32_e32 v0, 0xbfb8aa3b, v0
	v_exp_f32_e32 v0, v0
	v_lshl_add_u64 v[144:145], v[152:153], 0, v[144:145]
	v_add_f32_e32 v0, 1.0, v0
	v_rcp_f32_e32 v141, v0
	v_lshlrev_b32_e32 v0, 16, v142
	v_med3_f32 v0, v0, s14, v218
	v_mul_f32_e32 v0, 0xbfb8aa3b, v0
	v_exp_f32_e32 v0, v0
	v_pk_mul_f32 v[140:141], v[90:91], v[140:141]
	v_add_f32_e32 v0, 1.0, v0
	v_cvt_pk_bf16_f32 v139, v140, v141
	v_rcp_f32_e32 v140, v0
	v_and_b32_e32 v0, 0xffff0000, v142
	v_med3_f32 v0, v0, s14, v218
	v_mul_f32_e32 v0, 0xbfb8aa3b, v0
	v_exp_f32_e32 v0, v0
	s_nop 0
	v_add_f32_e32 v0, 1.0, v0
	v_rcp_f32_e32 v141, v0
	v_lshlrev_b32_e32 v0, 16, v143
	v_med3_f32 v0, v0, s14, v218
	v_mul_f32_e32 v0, 0xbfb8aa3b, v0
	v_exp_f32_e32 v0, v0
	v_pk_mul_f32 v[140:141], v[84:85], v[140:141]
	v_add_f32_e32 v0, 1.0, v0
	v_rcp_f32_e32 v142, v0
	v_and_b32_e32 v0, 0xffff0000, v143
	v_med3_f32 v0, v0, s14, v218
	v_mul_f32_e32 v0, 0xbfb8aa3b, v0
	v_exp_f32_e32 v0, v0
	v_cvt_pk_bf16_f32 v140, v140, v141
	v_add_f32_e32 v0, 1.0, v0
	v_rcp_f32_e32 v143, v0
	s_waitcnt vmcnt(0) lgkmcnt(0)
	v_lshlrev_b32_e32 v0, 16, v148
	v_med3_f32 v0, v0, s14, v218
	v_mul_f32_e32 v0, 0xbfb8aa3b, v0
	v_exp_f32_e32 v0, v0
	v_pk_mul_f32 v[142:143], v[86:87], v[142:143]
	v_add_f32_e32 v0, 1.0, v0
	v_rcp_f32_e32 v146, v0
	v_and_b32_e32 v0, 0xffff0000, v148
	v_med3_f32 v0, v0, s14, v218
	v_mul_f32_e32 v0, 0xbfb8aa3b, v0
	v_exp_f32_e32 v0, v0
	v_cvt_pk_bf16_f32 v141, v142, v143
	flat_store_dwordx4 v[136:137], v[138:141] offset:256
	v_lshlrev_b64 v[136:137], 8, v[160:161]
	v_add_f32_e32 v0, 1.0, v0
	v_rcp_f32_e32 v147, v0
	v_lshlrev_b32_e32 v0, 16, v149
	v_med3_f32 v0, v0, s14, v218
	v_mul_f32_e32 v0, 0xbfb8aa3b, v0
	v_exp_f32_e32 v0, v0
	v_pk_mul_f32 v[146:147], v[80:81], v[146:147]
	v_lshl_add_u64 v[136:137], v[158:159], 0, v[136:137]
	v_cvt_pk_bf16_f32 v146, v146, v147
	v_add_f32_e32 v0, 1.0, v0
	v_rcp_f32_e32 v148, v0
	v_and_b32_e32 v0, 0xffff0000, v149
	v_med3_f32 v0, v0, s14, v218
	v_mul_f32_e32 v0, 0xbfb8aa3b, v0
	v_exp_f32_e32 v0, v0
	v_lshl_add_u64 v[138:139], v[136:137], 0, v[154:155]
	flat_load_dwordx4 v[140:143], v[138:139]
	v_add_f32_e32 v0, 1.0, v0
	v_rcp_f32_e32 v149, v0
	v_lshlrev_b32_e32 v0, 16, v150
	v_med3_f32 v0, v0, s14, v218
	v_mul_f32_e32 v0, 0xbfb8aa3b, v0
	v_exp_f32_e32 v0, v0
	v_pk_mul_f32 v[148:149], v[82:83], v[148:149]
	v_lshl_add_u64 v[136:137], v[136:137], 0, v[156:157]
	v_cvt_pk_bf16_f32 v147, v148, v149
	v_add_f32_e32 v0, 1.0, v0
	v_rcp_f32_e32 v148, v0
	v_and_b32_e32 v0, 0xffff0000, v150
	v_med3_f32 v0, v0, s14, v218
	v_mul_f32_e32 v0, 0xbfb8aa3b, v0
	v_exp_f32_e32 v0, v0
	flat_load_dwordx4 v[136:139], v[136:137]
	v_add_f32_e32 v0, 1.0, v0
	v_rcp_f32_e32 v149, v0
	v_lshlrev_b32_e32 v0, 16, v151
	v_med3_f32 v0, v0, s14, v218
	v_mul_f32_e32 v0, 0xbfb8aa3b, v0
	v_exp_f32_e32 v0, v0
	v_pk_mul_f32 v[148:149], v[76:77], v[148:149]
	v_add_f32_e32 v0, 1.0, v0
	v_rcp_f32_e32 v150, v0
	v_and_b32_e32 v0, 0xffff0000, v151
	v_med3_f32 v0, v0, s14, v218
	v_mul_f32_e32 v0, 0xbfb8aa3b, v0
	v_exp_f32_e32 v0, v0
	v_cvt_pk_bf16_f32 v148, v148, v149
	v_add_f32_e32 v0, 1.0, v0
	v_rcp_f32_e32 v151, v0
	v_lshlrev_b32_e32 v0, 16, v132
	v_med3_f32 v0, v0, s14, v218
	v_mul_f32_e32 v0, 0xbfb8aa3b, v0
	v_exp_f32_e32 v0, v0
	v_pk_mul_f32 v[150:151], v[78:79], v[150:151]
	v_add_f32_e32 v0, 1.0, v0
	v_cvt_pk_bf16_f32 v149, v150, v151
	flat_store_dwordx4 v[144:145], v[146:149]
	v_lshlrev_b64 v[150:151], 12, v[160:161]
	v_lshl_add_u64 v[150:151], v[152:153], 0, v[150:151]
	v_rcp_f32_e32 v146, v0
	v_and_b32_e32 v0, 0xffff0000, v132
	v_med3_f32 v0, v0, s14, v218
	v_mul_f32_e32 v0, 0xbfb8aa3b, v0
	v_exp_f32_e32 v0, v0
	v_add_u32_e32 v148, 0x90, v2
	v_ashrrev_i32_e32 v149, 31, v148
	v_add_f32_e32 v0, 1.0, v0
	v_rcp_f32_e32 v147, v0
	v_lshlrev_b32_e32 v0, 16, v133
	v_med3_f32 v0, v0, s14, v218
	v_mul_f32_e32 v0, 0xbfb8aa3b, v0
	v_exp_f32_e32 v0, v0
	v_pk_mul_f32 v[146:147], v[72:73], v[146:147]
	v_add_f32_e32 v0, 1.0, v0
	v_cvt_pk_bf16_f32 v132, v146, v147
	v_rcp_f32_e32 v146, v0
	v_and_b32_e32 v0, 0xffff0000, v133
	v_med3_f32 v0, v0, s14, v218
	v_mul_f32_e32 v0, 0xbfb8aa3b, v0
	v_exp_f32_e32 v0, v0
	s_nop 0
	v_add_f32_e32 v0, 1.0, v0
	v_rcp_f32_e32 v147, v0
	v_lshlrev_b32_e32 v0, 16, v134
	v_med3_f32 v0, v0, s14, v218
	v_mul_f32_e32 v0, 0xbfb8aa3b, v0
	v_exp_f32_e32 v0, v0
	v_pk_mul_f32 v[146:147], v[74:75], v[146:147]
	v_add_f32_e32 v0, 1.0, v0
	v_cvt_pk_bf16_f32 v133, v146, v147
	v_rcp_f32_e32 v146, v0
	v_and_b32_e32 v0, 0xffff0000, v134
	v_med3_f32 v0, v0, s14, v218
	v_mul_f32_e32 v0, 0xbfb8aa3b, v0
	v_exp_f32_e32 v0, v0
	s_nop 0
	v_add_f32_e32 v0, 1.0, v0
	v_rcp_f32_e32 v147, v0
	v_lshlrev_b32_e32 v0, 16, v135
	v_med3_f32 v0, v0, s14, v218
	v_mul_f32_e32 v0, 0xbfb8aa3b, v0
	v_exp_f32_e32 v0, v0
	v_pk_mul_f32 v[146:147], v[68:69], v[146:147]
	v_add_f32_e32 v0, 1.0, v0
	v_cvt_pk_bf16_f32 v134, v146, v147
	v_rcp_f32_e32 v146, v0
	v_and_b32_e32 v0, 0xffff0000, v135
	v_med3_f32 v0, v0, s14, v218
	v_mul_f32_e32 v0, 0xbfb8aa3b, v0
	v_exp_f32_e32 v0, v0
	s_nop 0
	v_add_f32_e32 v0, 1.0, v0
	v_rcp_f32_e32 v147, v0
	s_waitcnt vmcnt(0) lgkmcnt(0)
; __device__ __forceinline__ unsigned pk2(float lo, float hi) { const f32v2_t v = {lo, hi}; return __builtin_bit_cast(unsigned, __builtin_convertvector(v, bf16v2_t)); }
; __device__ __forceinline__ float bflo(unsigned u) { return __uint_as_float(u << 16); }
; __device__ __forceinline__ float bfhi(unsigned u) { return __uint_as_float(u & 0xffff0000u); }
; #define M1_LD(it, bf) do { const int gr = row0 + ((it) >> 2) * 128 + ((it) & 3) * 16; \
;             _Pragma("unroll") for (int bj = 0; bj < 2; ++bj) gb[bf][bj] = *(const u32x4*)(P + pidx(gr, gc2 + bj * 128)); } while (0)
; __device__ __forceinline__ float sigc(float x) { return __builtin_amdgcn_rcpf(1.f + __expf(-fminf(fmaxf(x, -30.f), 30.f))); }
;     __device__ __forceinline__ void operator()(const f32x4 (&acc)[2][2][4][2], const pg8::Unit& u, int wr, int wc, int fr, int fq) const {
;     ...
;             M1_LD(0, 0);
; #pragma unroll
;             for (int it = 0; it < 8; ++it) {
;                 if (it < 7) M1_LD(it + 1, (it + 1) & 1);
;                 const int ai = it >> 2, m = it & 3, row = row0 + ai * 128 + m * 16;
; #pragma unroll
;                 for (int bj = 0; bj < 2; ++bj) {
;                     const u32x4 gw = gb[it & 1][bj];
;                     const f32x4 a0 = acc[ai][bj][m][0], a1 = acc[ai][bj][m][1];
;                     u32x4 o = {pk2(sigc(bflo(gw[0])) * a0[0], sigc(bfhi(gw[0])) * a0[1]), pk2(sigc(bflo(gw[1])) * a0[2], sigc(bfhi(gw[1])) * a0[3]),
;                                pk2(sigc(bflo(gw[2])) * a1[0], sigc(bfhi(gw[2])) * a1[1]), pk2(sigc(bflo(gw[3])) * a1[2], sigc(bfhi(gw[3])) * a1[3])};
;                     *(u32x4*)(YB + (size_t)row * D + col0 + bj * 128) = o;
;                 }
;                 asm volatile("" ::: "memory");
;             }
	v_lshlrev_b32_e32 v0, 16, v140
	v_med3_f32 v0, v0, s14, v218
	v_mul_f32_e32 v0, 0xbfb8aa3b, v0
	v_exp_f32_e32 v0, v0
	v_pk_mul_f32 v[146:147], v[70:71], v[146:147]
	v_add_f32_e32 v0, 1.0, v0
	v_rcp_f32_e32 v160, v0
	v_and_b32_e32 v0, 0xffff0000, v140
	v_med3_f32 v0, v0, s14, v218
	v_mul_f32_e32 v0, 0xbfb8aa3b, v0
	v_exp_f32_e32 v0, v0
	v_cvt_pk_bf16_f32 v135, v146, v147
	flat_store_dwordx4 v[144:145], v[132:135] offset:256
	v_add_f32_e32 v0, 1.0, v0
	v_rcp_f32_e32 v161, v0
	v_lshlrev_b32_e32 v0, 16, v141
	v_med3_f32 v0, v0, s14, v218
	v_mul_f32_e32 v0, 0xbfb8aa3b, v0
	v_exp_f32_e32 v0, v0
	v_pk_mul_f32 v[160:161], v[64:65], v[160:161]
	v_lshlrev_b64 v[132:133], 8, v[148:149]
	v_cvt_pk_bf16_f32 v140, v160, v161
	v_add_f32_e32 v0, 1.0, v0
	v_rcp_f32_e32 v160, v0
	v_and_b32_e32 v0, 0xffff0000, v141
	v_med3_f32 v0, v0, s14, v218
	v_mul_f32_e32 v0, 0xbfb8aa3b, v0
	v_exp_f32_e32 v0, v0
	v_lshl_add_u64 v[132:133], v[158:159], 0, v[132:133]
	v_lshl_add_u64 v[134:135], v[132:133], 0, v[154:155]
	flat_load_dwordx4 v[144:147], v[134:135]
	v_add_f32_e32 v0, 1.0, v0
	v_rcp_f32_e32 v161, v0
	v_lshlrev_b32_e32 v0, 16, v142
	v_med3_f32 v0, v0, s14, v218
	v_mul_f32_e32 v0, 0xbfb8aa3b, v0
	v_exp_f32_e32 v0, v0
	v_pk_mul_f32 v[160:161], v[66:67], v[160:161]
	v_lshl_add_u64 v[132:133], v[132:133], 0, v[156:157]
	v_cvt_pk_bf16_f32 v141, v160, v161
	v_add_f32_e32 v0, 1.0, v0
	v_rcp_f32_e32 v160, v0
	v_and_b32_e32 v0, 0xffff0000, v142
	v_med3_f32 v0, v0, s14, v218
	v_mul_f32_e32 v0, 0xbfb8aa3b, v0
	v_exp_f32_e32 v0, v0
	flat_load_dwordx4 v[132:135], v[132:133]
	v_lshlrev_b64 v[148:149], 12, v[148:149]
	v_lshl_add_u64 v[148:149], v[152:153], 0, v[148:149]
	v_add_f32_e32 v0, 1.0, v0
	v_rcp_f32_e32 v161, v0
	v_lshlrev_b32_e32 v0, 16, v143
	v_med3_f32 v0, v0, s14, v218
	v_mul_f32_e32 v0, 0xbfb8aa3b, v0
	v_exp_f32_e32 v0, v0
	v_pk_mul_f32 v[160:161], v[60:61], v[160:161]
	v_add_f32_e32 v0, 1.0, v0
	v_cvt_pk_bf16_f32 v142, v160, v161
	v_rcp_f32_e32 v160, v0
	v_and_b32_e32 v0, 0xffff0000, v143
	v_med3_f32 v0, v0, s14, v218
	v_mul_f32_e32 v0, 0xbfb8aa3b, v0
	v_exp_f32_e32 v0, v0
	s_nop 0
	v_add_f32_e32 v0, 1.0, v0
	v_rcp_f32_e32 v161, v0
	v_lshlrev_b32_e32 v0, 16, v136
	v_med3_f32 v0, v0, s14, v218
	v_mul_f32_e32 v0, 0xbfb8aa3b, v0
	v_exp_f32_e32 v0, v0
	v_pk_mul_f32 v[160:161], v[62:63], v[160:161]
	v_add_f32_e32 v0, 1.0, v0
	v_cvt_pk_bf16_f32 v143, v160, v161
	flat_store_dwordx4 v[150:151], v[140:143]
	s_nop 1
	v_rcp_f32_e32 v140, v0
	v_and_b32_e32 v0, 0xffff0000, v136
	v_med3_f32 v0, v0, s14, v218
	v_mul_f32_e32 v0, 0xbfb8aa3b, v0
	v_exp_f32_e32 v0, v0
	s_nop 0
	v_add_f32_e32 v0, 1.0, v0
	v_rcp_f32_e32 v141, v0
	v_lshlrev_b32_e32 v0, 16, v137
	v_med3_f32 v0, v0, s14, v218
	v_mul_f32_e32 v0, 0xbfb8aa3b, v0
	v_exp_f32_e32 v0, v0
	v_pk_mul_f32 v[140:141], v[56:57], v[140:141]
	v_add_f32_e32 v0, 1.0, v0
	v_cvt_pk_bf16_f32 v136, v140, v141
	v_rcp_f32_e32 v140, v0
	v_and_b32_e32 v0, 0xffff0000, v137
	v_med3_f32 v0, v0, s14, v218
	v_mul_f32_e32 v0, 0xbfb8aa3b, v0
	v_exp_f32_e32 v0, v0
	s_nop 0
	v_add_f32_e32 v0, 1.0, v0
	v_rcp_f32_e32 v141, v0
	v_lshlrev_b32_e32 v0, 16, v138
	v_med3_f32 v0, v0, s14, v218
	v_mul_f32_e32 v0, 0xbfb8aa3b, v0
	v_exp_f32_e32 v0, v0
	v_pk_mul_f32 v[140:141], v[58:59], v[140:141]
	v_add_f32_e32 v0, 1.0, v0
	v_cvt_pk_bf16_f32 v137, v140, v141
	v_rcp_f32_e32 v140, v0
	v_and_b32_e32 v0, 0xffff0000, v138
	v_med3_f32 v0, v0, s14, v218
	v_mul_f32_e32 v0, 0xbfb8aa3b, v0
	v_exp_f32_e32 v0, v0
	s_nop 0
	v_add_f32_e32 v0, 1.0, v0
	v_rcp_f32_e32 v141, v0
	v_lshlrev_b32_e32 v0, 16, v139
	v_med3_f32 v0, v0, s14, v218
	v_mul_f32_e32 v0, 0xbfb8aa3b, v0
	v_exp_f32_e32 v0, v0
	v_pk_mul_f32 v[140:141], v[52:53], v[140:141]
	v_add_f32_e32 v0, 1.0, v0
	v_cvt_pk_bf16_f32 v138, v140, v141
	v_rcp_f32_e32 v140, v0
	v_and_b32_e32 v0, 0xffff0000, v139
	v_med3_f32 v0, v0, s14, v218
	v_mul_f32_e32 v0, 0xbfb8aa3b, v0
	v_exp_f32_e32 v0, v0
	s_nop 0
	v_add_f32_e32 v0, 1.0, v0
	v_rcp_f32_e32 v141, v0
	s_waitcnt vmcnt(0) lgkmcnt(0)
	v_lshlrev_b32_e32 v0, 16, v144
	v_med3_f32 v0, v0, s14, v218
	v_mul_f32_e32 v0, 0xbfb8aa3b, v0
	v_exp_f32_e32 v0, v0
	v_pk_mul_f32 v[140:141], v[54:55], v[140:141]
	v_add_f32_e32 v0, 1.0, v0
	v_rcp_f32_e32 v160, v0
	v_and_b32_e32 v0, 0xffff0000, v144
	v_med3_f32 v0, v0, s14, v218
	v_mul_f32_e32 v0, 0xbfb8aa3b, v0
	v_exp_f32_e32 v0, v0
	v_cvt_pk_bf16_f32 v139, v140, v141
	flat_store_dwordx4 v[150:151], v[136:139] offset:256
	v_add_u32_e32 v150, 0xa0, v2
	v_add_f32_e32 v0, 1.0, v0
	v_rcp_f32_e32 v161, v0
	v_lshlrev_b32_e32 v0, 16, v145
	v_med3_f32 v0, v0, s14, v218
	v_mul_f32_e32 v0, 0xbfb8aa3b, v0
	v_exp_f32_e32 v0, v0
	v_pk_mul_f32 v[160:161], v[48:49], v[160:161]
	v_ashrrev_i32_e32 v151, 31, v150
	v_cvt_pk_bf16_f32 v144, v160, v161
	v_add_f32_e32 v0, 1.0, v0
	v_rcp_f32_e32 v160, v0
	v_and_b32_e32 v0, 0xffff0000, v145
	v_med3_f32 v0, v0, s14, v218
	v_mul_f32_e32 v0, 0xbfb8aa3b, v0
	v_exp_f32_e32 v0, v0
	v_lshlrev_b64 v[136:137], 8, v[150:151]
	v_lshl_add_u64 v[136:137], v[158:159], 0, v[136:137]
	v_add_f32_e32 v0, 1.0, v0
	v_rcp_f32_e32 v161, v0
	v_lshlrev_b32_e32 v0, 16, v146
	v_med3_f32 v0, v0, s14, v218
	v_mul_f32_e32 v0, 0xbfb8aa3b, v0
	v_exp_f32_e32 v0, v0
	v_pk_mul_f32 v[160:161], v[50:51], v[160:161]
	v_lshl_add_u64 v[138:139], v[136:137], 0, v[154:155]
	v_cvt_pk_bf16_f32 v145, v160, v161
	v_add_f32_e32 v0, 1.0, v0
	v_rcp_f32_e32 v160, v0
	v_and_b32_e32 v0, 0xffff0000, v146
	v_med3_f32 v0, v0, s14, v218
	v_mul_f32_e32 v0, 0xbfb8aa3b, v0
	v_exp_f32_e32 v0, v0
	flat_load_dwordx4 v[140:143], v[138:139]
	v_lshl_add_u64 v[136:137], v[136:137], 0, v[156:157]
	flat_load_dwordx4 v[136:139], v[136:137]
	v_add_f32_e32 v0, 1.0, v0
	v_rcp_f32_e32 v161, v0
; __device__ __forceinline__ unsigned pk2(float lo, float hi) { const f32v2_t v = {lo, hi}; return __builtin_bit_cast(unsigned, __builtin_convertvector(v, bf16v2_t)); }
; __device__ __forceinline__ float bflo(unsigned u) { return __uint_as_float(u << 16); }
; __device__ __forceinline__ float bfhi(unsigned u) { return __uint_as_float(u & 0xffff0000u); }
; #define M1_LD(it, bf) do { const int gr = row0 + ((it) >> 2) * 128 + ((it) & 3) * 16; \
;             _Pragma("unroll") for (int bj = 0; bj < 2; ++bj) gb[bf][bj] = *(const u32x4*)(P + pidx(gr, gc2 + bj * 128)); } while (0)
; __device__ __forceinline__ float sigc(float x) { return __builtin_amdgcn_rcpf(1.f + __expf(-fminf(fmaxf(x, -30.f), 30.f))); }
;     __device__ __forceinline__ void operator()(const f32x4 (&acc)[2][2][4][2], const pg8::Unit& u, int wr, int wc, int fr, int fq) const {
;     ...
;             M1_LD(0, 0);
; #pragma unroll
;             for (int it = 0; it < 8; ++it) {
;                 if (it < 7) M1_LD(it + 1, (it + 1) & 1);
;                 const int ai = it >> 2, m = it & 3, row = row0 + ai * 128 + m * 16;
; #pragma unroll
;                 for (int bj = 0; bj < 2; ++bj) {
;                     const u32x4 gw = gb[it & 1][bj];
;                     const f32x4 a0 = acc[ai][bj][m][0], a1 = acc[ai][bj][m][1];
;                     u32x4 o = {pk2(sigc(bflo(gw[0])) * a0[0], sigc(bfhi(gw[0])) * a0[1]), pk2(sigc(bflo(gw[1])) * a0[2], sigc(bfhi(gw[1])) * a0[3]),
;                                pk2(sigc(bflo(gw[2])) * a1[0], sigc(bfhi(gw[2])) * a1[1]), pk2(sigc(bflo(gw[3])) * a1[2], sigc(bfhi(gw[3])) * a1[3])};
;                     *(u32x4*)(YB + (size_t)row * D + col0 + bj * 128) = o;
;                 }
;                 asm volatile("" ::: "memory");
;             }
	v_lshlrev_b32_e32 v0, 16, v147
	v_med3_f32 v0, v0, s14, v218
	v_mul_f32_e32 v0, 0xbfb8aa3b, v0
	v_exp_f32_e32 v0, v0
	v_pk_mul_f32 v[160:161], v[44:45], v[160:161]
	v_lshlrev_b64 v[150:151], 12, v[150:151]
	v_cvt_pk_bf16_f32 v146, v160, v161
	v_add_f32_e32 v0, 1.0, v0
	v_rcp_f32_e32 v160, v0
	v_and_b32_e32 v0, 0xffff0000, v147
	v_med3_f32 v0, v0, s14, v218
	v_mul_f32_e32 v0, 0xbfb8aa3b, v0
	v_exp_f32_e32 v0, v0
	v_lshl_add_u64 v[150:151], v[152:153], 0, v[150:151]
	v_add_f32_e32 v0, 1.0, v0
	v_rcp_f32_e32 v161, v0
	v_lshlrev_b32_e32 v0, 16, v132
	v_med3_f32 v0, v0, s14, v218
	v_mul_f32_e32 v0, 0xbfb8aa3b, v0
	v_exp_f32_e32 v0, v0
	v_pk_mul_f32 v[160:161], v[46:47], v[160:161]
	v_add_f32_e32 v0, 1.0, v0
	v_cvt_pk_bf16_f32 v147, v160, v161
	flat_store_dwordx4 v[148:149], v[144:147]
	s_nop 1
	v_rcp_f32_e32 v144, v0
	v_and_b32_e32 v0, 0xffff0000, v132
	v_med3_f32 v0, v0, s14, v218
	v_mul_f32_e32 v0, 0xbfb8aa3b, v0
	v_exp_f32_e32 v0, v0
	s_nop 0
	v_add_f32_e32 v0, 1.0, v0
	v_rcp_f32_e32 v145, v0
	v_lshlrev_b32_e32 v0, 16, v133
	v_med3_f32 v0, v0, s14, v218
	v_mul_f32_e32 v0, 0xbfb8aa3b, v0
	v_exp_f32_e32 v0, v0
	v_pk_mul_f32 v[144:145], v[40:41], v[144:145]
	v_add_f32_e32 v0, 1.0, v0
	v_cvt_pk_bf16_f32 v132, v144, v145
	v_rcp_f32_e32 v144, v0
	v_and_b32_e32 v0, 0xffff0000, v133
	v_med3_f32 v0, v0, s14, v218
	v_mul_f32_e32 v0, 0xbfb8aa3b, v0
	v_exp_f32_e32 v0, v0
	s_nop 0
	v_add_f32_e32 v0, 1.0, v0
	v_rcp_f32_e32 v145, v0
	v_lshlrev_b32_e32 v0, 16, v134
	v_med3_f32 v0, v0, s14, v218
	v_mul_f32_e32 v0, 0xbfb8aa3b, v0
	v_exp_f32_e32 v0, v0
	v_pk_mul_f32 v[144:145], v[42:43], v[144:145]
	v_add_f32_e32 v0, 1.0, v0
	v_cvt_pk_bf16_f32 v133, v144, v145
	v_rcp_f32_e32 v144, v0
	v_and_b32_e32 v0, 0xffff0000, v134
	v_med3_f32 v0, v0, s14, v218
	v_mul_f32_e32 v0, 0xbfb8aa3b, v0
	v_exp_f32_e32 v0, v0
	s_nop 0
	v_add_f32_e32 v0, 1.0, v0
	v_rcp_f32_e32 v145, v0
	v_lshlrev_b32_e32 v0, 16, v135
	v_med3_f32 v0, v0, s14, v218
	v_mul_f32_e32 v0, 0xbfb8aa3b, v0
	v_exp_f32_e32 v0, v0
	v_pk_mul_f32 v[144:145], v[36:37], v[144:145]
	v_add_f32_e32 v0, 1.0, v0
	v_cvt_pk_bf16_f32 v134, v144, v145
	v_rcp_f32_e32 v144, v0
	v_and_b32_e32 v0, 0xffff0000, v135
	v_med3_f32 v0, v0, s14, v218
	v_mul_f32_e32 v0, 0xbfb8aa3b, v0
	v_exp_f32_e32 v0, v0
	s_nop 0
	v_add_f32_e32 v0, 1.0, v0
	v_rcp_f32_e32 v145, v0
	s_waitcnt vmcnt(0) lgkmcnt(0)
	v_lshlrev_b32_e32 v0, 16, v140
	v_med3_f32 v0, v0, s14, v218
	v_pk_mul_f32 v[144:145], v[38:39], v[144:145]
	v_mul_f32_e32 v0, 0xbfb8aa3b, v0
	v_cvt_pk_bf16_f32 v135, v144, v145
	v_exp_f32_e32 v0, v0
	flat_store_dwordx4 v[148:149], v[132:135] offset:256
	v_add_u32_e32 v148, 0xb0, v2
	v_ashrrev_i32_e32 v149, 31, v148
	v_lshlrev_b64 v[132:133], 8, v[148:149]
	v_lshl_add_u64 v[132:133], v[158:159], 0, v[132:133]
	v_add_f32_e32 v0, 1.0, v0
	v_lshl_add_u64 v[134:135], v[132:133], 0, v[154:155]
	v_rcp_f32_e32 v154, v0
	v_and_b32_e32 v0, 0xffff0000, v140
	v_med3_f32 v0, v0, s14, v218
	v_mul_f32_e32 v0, 0xbfb8aa3b, v0
	v_exp_f32_e32 v0, v0
	flat_load_dwordx4 v[144:147], v[134:135]
	v_lshl_add_u64 v[132:133], v[132:133], 0, v[156:157]
	v_add_f32_e32 v0, 1.0, v0
	v_rcp_f32_e32 v155, v0
	v_lshlrev_b32_e32 v0, 16, v141
	v_med3_f32 v0, v0, s14, v218
	v_mul_f32_e32 v0, 0xbfb8aa3b, v0
	v_exp_f32_e32 v0, v0
	v_pk_mul_f32 v[154:155], v[32:33], v[154:155]
	flat_load_dwordx4 v[132:135], v[132:133]
	v_cvt_pk_bf16_f32 v140, v154, v155
	v_add_f32_e32 v0, 1.0, v0
	v_rcp_f32_e32 v154, v0
	v_and_b32_e32 v0, 0xffff0000, v141
	v_med3_f32 v0, v0, s14, v218
	v_mul_f32_e32 v0, 0xbfb8aa3b, v0
	v_exp_f32_e32 v0, v0
	s_nop 0
	v_add_f32_e32 v0, 1.0, v0
	v_rcp_f32_e32 v155, v0
	v_lshlrev_b32_e32 v0, 16, v142
	v_med3_f32 v0, v0, s14, v218
	v_mul_f32_e32 v0, 0xbfb8aa3b, v0
	v_exp_f32_e32 v0, v0
	v_pk_mul_f32 v[154:155], v[34:35], v[154:155]
	v_add_f32_e32 v0, 1.0, v0
	v_cvt_pk_bf16_f32 v141, v154, v155
	v_rcp_f32_e32 v154, v0
	v_and_b32_e32 v0, 0xffff0000, v142
	v_med3_f32 v0, v0, s14, v218
	v_mul_f32_e32 v0, 0xbfb8aa3b, v0
	v_exp_f32_e32 v0, v0
	s_nop 0
	v_add_f32_e32 v0, 1.0, v0
	v_rcp_f32_e32 v155, v0
	v_lshlrev_b32_e32 v0, 16, v143
	v_med3_f32 v0, v0, s14, v218
	v_mul_f32_e32 v0, 0xbfb8aa3b, v0
	v_exp_f32_e32 v0, v0
	v_pk_mul_f32 v[154:155], v[28:29], v[154:155]
	v_add_f32_e32 v0, 1.0, v0
	v_cvt_pk_bf16_f32 v142, v154, v155
	v_rcp_f32_e32 v154, v0
	v_and_b32_e32 v0, 0xffff0000, v143
	v_med3_f32 v0, v0, s14, v218
	v_mul_f32_e32 v0, 0xbfb8aa3b, v0
	v_exp_f32_e32 v0, v0
	s_nop 0
	v_add_f32_e32 v0, 1.0, v0
	v_rcp_f32_e32 v155, v0
	v_lshlrev_b32_e32 v0, 16, v136
	v_med3_f32 v0, v0, s14, v218
	v_mul_f32_e32 v0, 0xbfb8aa3b, v0
	v_exp_f32_e32 v0, v0
	v_pk_mul_f32 v[154:155], v[30:31], v[154:155]
	v_add_f32_e32 v0, 1.0, v0
	v_cvt_pk_bf16_f32 v143, v154, v155
	flat_store_dwordx4 v[150:151], v[140:143]
	s_nop 1
	v_rcp_f32_e32 v140, v0
	v_and_b32_e32 v0, 0xffff0000, v136
	v_med3_f32 v0, v0, s14, v218
	v_mul_f32_e32 v0, 0xbfb8aa3b, v0
	v_exp_f32_e32 v0, v0
	s_nop 0
	v_add_f32_e32 v0, 1.0, v0
	v_rcp_f32_e32 v141, v0
	v_lshlrev_b32_e32 v0, 16, v137
	v_med3_f32 v0, v0, s14, v218
	v_mul_f32_e32 v0, 0xbfb8aa3b, v0
	v_exp_f32_e32 v0, v0
	v_pk_mul_f32 v[140:141], v[24:25], v[140:141]
	v_add_f32_e32 v0, 1.0, v0
	v_cvt_pk_bf16_f32 v136, v140, v141
	v_rcp_f32_e32 v140, v0
	v_and_b32_e32 v0, 0xffff0000, v137
	v_med3_f32 v0, v0, s14, v218
	v_mul_f32_e32 v0, 0xbfb8aa3b, v0
	v_exp_f32_e32 v0, v0
	s_nop 0
	v_add_f32_e32 v0, 1.0, v0
	v_rcp_f32_e32 v141, v0
	v_lshlrev_b32_e32 v0, 16, v138
	v_med3_f32 v0, v0, s14, v218
	v_mul_f32_e32 v0, 0xbfb8aa3b, v0
	v_exp_f32_e32 v0, v0
	v_pk_mul_f32 v[140:141], v[26:27], v[140:141]
	v_add_f32_e32 v0, 1.0, v0
	v_cvt_pk_bf16_f32 v137, v140, v141
	v_rcp_f32_e32 v140, v0
	v_and_b32_e32 v0, 0xffff0000, v138
	v_med3_f32 v0, v0, s14, v218
	v_mul_f32_e32 v0, 0xbfb8aa3b, v0
	v_exp_f32_e32 v0, v0
	s_nop 0
	v_add_f32_e32 v0, 1.0, v0
	v_rcp_f32_e32 v141, v0
	v_lshlrev_b32_e32 v0, 16, v139
	v_med3_f32 v0, v0, s14, v218
	v_mul_f32_e32 v0, 0xbfb8aa3b, v0
	v_exp_f32_e32 v0, v0
	v_pk_mul_f32 v[140:141], v[20:21], v[140:141]
	v_add_f32_e32 v0, 1.0, v0
	v_cvt_pk_bf16_f32 v138, v140, v141
	v_rcp_f32_e32 v140, v0
	v_and_b32_e32 v0, 0xffff0000, v139
	v_med3_f32 v0, v0, s14, v218
	v_mul_f32_e32 v0, 0xbfb8aa3b, v0
	v_exp_f32_e32 v0, v0
	s_nop 0
	v_add_f32_e32 v0, 1.0, v0
	v_rcp_f32_e32 v141, v0
	s_waitcnt vmcnt(0) lgkmcnt(0)
; __device__ __forceinline__ unsigned pk2(float lo, float hi) { const f32v2_t v = {lo, hi}; return __builtin_bit_cast(unsigned, __builtin_convertvector(v, bf16v2_t)); }
; __device__ __forceinline__ float bflo(unsigned u) { return __uint_as_float(u << 16); }
; __device__ __forceinline__ float bfhi(unsigned u) { return __uint_as_float(u & 0xffff0000u); }
; #define M1_LD(it, bf) do { const int gr = row0 + ((it) >> 2) * 128 + ((it) & 3) * 16; \
;             _Pragma("unroll") for (int bj = 0; bj < 2; ++bj) gb[bf][bj] = *(const u32x4*)(P + pidx(gr, gc2 + bj * 128)); } while (0)
; __device__ __forceinline__ float sigc(float x) { return __builtin_amdgcn_rcpf(1.f + __expf(-fminf(fmaxf(x, -30.f), 30.f))); }
;     __device__ __forceinline__ void operator()(const f32x4 (&acc)[2][2][4][2], const pg8::Unit& u, int wr, int wc, int fr, int fq) const {
;     ...
;             M1_LD(0, 0);
; #pragma unroll
;             for (int it = 0; it < 8; ++it) {
;                 if (it < 7) M1_LD(it + 1, (it + 1) & 1);
;                 const int ai = it >> 2, m = it & 3, row = row0 + ai * 128 + m * 16;
; #pragma unroll
;                 for (int bj = 0; bj < 2; ++bj) {
;                     const u32x4 gw = gb[it & 1][bj];
;                     const f32x4 a0 = acc[ai][bj][m][0], a1 = acc[ai][bj][m][1];
;                     u32x4 o = {pk2(sigc(bflo(gw[0])) * a0[0], sigc(bfhi(gw[0])) * a0[1]), pk2(sigc(bflo(gw[1])) * a0[2], sigc(bfhi(gw[1])) * a0[3]),
;                                pk2(sigc(bflo(gw[2])) * a1[0], sigc(bfhi(gw[2])) * a1[1]), pk2(sigc(bflo(gw[3])) * a1[2], sigc(bfhi(gw[3])) * a1[3])};
;                     *(u32x4*)(YB + (size_t)row * D + col0 + bj * 128) = o;
;                 }
;                 asm volatile("" ::: "memory");
;             }
	v_lshlrev_b32_e32 v0, 16, v144
	v_med3_f32 v0, v0, s14, v218
	v_mul_f32_e32 v0, 0xbfb8aa3b, v0
	v_exp_f32_e32 v0, v0
	v_pk_mul_f32 v[140:141], v[22:23], v[140:141]
	v_add_f32_e32 v0, 1.0, v0
	v_cvt_pk_bf16_f32 v139, v140, v141
	flat_store_dwordx4 v[150:151], v[136:139] offset:256
	s_nop 1
	v_rcp_f32_e32 v138, v0
	v_and_b32_e32 v0, 0xffff0000, v144
	v_med3_f32 v0, v0, s14, v218
	v_mul_f32_e32 v0, 0xbfb8aa3b, v0
	v_exp_f32_e32 v0, v0
	v_lshlrev_b64 v[136:137], 12, v[148:149]
	v_lshl_add_u64 v[136:137], v[152:153], 0, v[136:137]
	v_add_f32_e32 v0, 1.0, v0
	v_rcp_f32_e32 v139, v0
	v_lshlrev_b32_e32 v0, 16, v145
	v_med3_f32 v0, v0, s14, v218
	v_mul_f32_e32 v0, 0xbfb8aa3b, v0
	v_exp_f32_e32 v0, v0
	v_pk_mul_f32 v[138:139], v[16:17], v[138:139]
	v_add_f32_e32 v0, 1.0, v0
	v_rcp_f32_e32 v140, v0
	v_and_b32_e32 v0, 0xffff0000, v145
	v_med3_f32 v0, v0, s14, v218
	v_mul_f32_e32 v0, 0xbfb8aa3b, v0
	v_exp_f32_e32 v0, v0
	v_cvt_pk_bf16_f32 v138, v138, v139
	v_add_f32_e32 v0, 1.0, v0
	v_rcp_f32_e32 v141, v0
	v_lshlrev_b32_e32 v0, 16, v146
	v_med3_f32 v0, v0, s14, v218
	v_mul_f32_e32 v0, 0xbfb8aa3b, v0
	v_exp_f32_e32 v0, v0
	v_pk_mul_f32 v[140:141], v[18:19], v[140:141]
	v_add_f32_e32 v0, 1.0, v0
	v_cvt_pk_bf16_f32 v139, v140, v141
	v_rcp_f32_e32 v140, v0
	v_and_b32_e32 v0, 0xffff0000, v146
	v_med3_f32 v0, v0, s14, v218
	v_mul_f32_e32 v0, 0xbfb8aa3b, v0
	v_exp_f32_e32 v0, v0
	s_nop 0
	v_add_f32_e32 v0, 1.0, v0
	v_rcp_f32_e32 v141, v0
	v_lshlrev_b32_e32 v0, 16, v147
	v_med3_f32 v0, v0, s14, v218
	v_mul_f32_e32 v0, 0xbfb8aa3b, v0
	v_exp_f32_e32 v0, v0
	v_pk_mul_f32 v[140:141], v[12:13], v[140:141]
	v_add_f32_e32 v0, 1.0, v0
	v_rcp_f32_e32 v142, v0
	v_and_b32_e32 v0, 0xffff0000, v147
	v_med3_f32 v0, v0, s14, v218
	v_mul_f32_e32 v0, 0xbfb8aa3b, v0
	v_exp_f32_e32 v0, v0
	v_cvt_pk_bf16_f32 v140, v140, v141
	v_add_f32_e32 v0, 1.0, v0
	v_rcp_f32_e32 v143, v0
	v_lshlrev_b32_e32 v0, 16, v132
	v_med3_f32 v0, v0, s14, v218
	v_mul_f32_e32 v0, 0xbfb8aa3b, v0
	v_exp_f32_e32 v0, v0
	v_pk_mul_f32 v[142:143], v[14:15], v[142:143]
	v_add_f32_e32 v0, 1.0, v0
	v_cvt_pk_bf16_f32 v141, v142, v143
	flat_store_dwordx4 v[136:137], v[138:141]
	s_nop 1
	v_rcp_f32_e32 v138, v0
	v_and_b32_e32 v0, 0xffff0000, v132
	v_med3_f32 v0, v0, s14, v218
	v_mul_f32_e32 v0, 0xbfb8aa3b, v0
	v_exp_f32_e32 v0, v0
	s_nop 0
	v_add_f32_e32 v0, 1.0, v0
	v_rcp_f32_e32 v139, v0
	v_lshlrev_b32_e32 v0, 16, v133
	v_med3_f32 v0, v0, s14, v218
	v_mul_f32_e32 v0, 0xbfb8aa3b, v0
	v_exp_f32_e32 v0, v0
	v_pk_mul_f32 v[138:139], v[8:9], v[138:139]
	v_add_f32_e32 v0, 1.0, v0
	v_cvt_pk_bf16_f32 v132, v138, v139
	v_rcp_f32_e32 v138, v0
	v_and_b32_e32 v0, 0xffff0000, v133
	v_med3_f32 v0, v0, s14, v218
	v_mul_f32_e32 v0, 0xbfb8aa3b, v0
	v_exp_f32_e32 v0, v0
	s_nop 0
	v_add_f32_e32 v0, 1.0, v0
	v_rcp_f32_e32 v139, v0
	v_lshlrev_b32_e32 v0, 16, v134
	v_med3_f32 v0, v0, s14, v218
	v_mul_f32_e32 v0, 0xbfb8aa3b, v0
	v_exp_f32_e32 v0, v0
	v_pk_mul_f32 v[138:139], v[10:11], v[138:139]
	v_add_f32_e32 v0, 1.0, v0
	v_cvt_pk_bf16_f32 v133, v138, v139
	v_rcp_f32_e32 v138, v0
	v_and_b32_e32 v0, 0xffff0000, v134
	v_med3_f32 v0, v0, s14, v218
	v_mul_f32_e32 v0, 0xbfb8aa3b, v0
	v_exp_f32_e32 v0, v0
	s_nop 0
	v_add_f32_e32 v0, 1.0, v0
	v_rcp_f32_e32 v139, v0
	v_lshlrev_b32_e32 v0, 16, v135
	v_med3_f32 v0, v0, s14, v218
	v_mul_f32_e32 v0, 0xbfb8aa3b, v0
	v_exp_f32_e32 v0, v0
	v_pk_mul_f32 v[138:139], v[4:5], v[138:139]
	v_add_f32_e32 v0, 1.0, v0
	v_cvt_pk_bf16_f32 v134, v138, v139
	v_rcp_f32_e32 v138, v0
	v_and_b32_e32 v0, 0xffff0000, v135
	v_med3_f32 v0, v0, s14, v218
	v_mul_f32_e32 v0, 0xbfb8aa3b, v0
	v_exp_f32_e32 v0, v0
	s_nop 0
	v_add_f32_e32 v0, 1.0, v0
	v_rcp_f32_e32 v139, v0
	s_nop 0
	v_pk_mul_f32 v[138:139], v[6:7], v[138:139]
	s_nop 0
	v_cvt_pk_bf16_f32 v135, v138, v139
	flat_store_dwordx4 v[136:137], v[132:135] offset:256

; __device__ __forceinline__ unsigned xb_ld(unsigned* p)              { return __hip_atomic_load(p, __ATOMIC_RELAXED, __HIP_MEMORY_SCOPE_AGENT); }
;     __device__ __forceinline__ void fused(f32x4 (&acc)[2][2][4][2], const pg8::Unit& u, int wr, int wc, int fr, int fq, unsigned char* lds) const {
;     ...
;         __syncthreads();
;         if (tid < 256) {
;             float sum = 0.f;
; #pragma unroll
;             for (int j = 0; j < 8; ++j) sum += __uint_as_float(xb_ld(slot + tid * 8 + j));
;             invtab[tid] = rsqrtf(sum * (1.f / D) + EPS);
;         }
.LBB0_282:
	s_or_b64 exec, exec, s[36:37]
	s_barrier
	s_and_saveexec_b64 s[0:1], vcc
	s_cbranch_execz .LBB0_284
	v_lshl_add_u64 v[132:133], v[132:133], 2, s[2:3]
	flat_load_dword v224, v[132:133] sc1
	flat_load_dword v225, v[132:133] offset:4 sc1
	flat_load_dword v226, v[132:133] offset:8 sc1
	flat_load_dword v227, v[132:133] offset:12 sc1
	flat_load_dword v228, v[132:133] offset:16 sc1
	flat_load_dword v229, v[132:133] offset:20 sc1
	flat_load_dword v230, v[132:133] offset:24 sc1
	flat_load_dword v231, v[132:133] offset:28 sc1
	v_lshl_add_u32 v0, v0, 2, 0
	s_waitcnt vmcnt(0) lgkmcnt(0)
	v_add_f32_e32 v134, 0, v224
	v_add_f32_e32 v134, v134, v225
	v_add_f32_e32 v134, v134, v226
	v_add_f32_e32 v134, v134, v227
	v_add_f32_e32 v134, v134, v228
	v_add_f32_e32 v134, v134, v229
	v_add_f32_e32 v134, v134, v230
	v_add_f32_e32 v132, v134, v231
	v_fmamk_f32 v132, v132, 0x3a000000, v184
	v_cmp_gt_f32_e32 vcc, s90, v132
	v_mul_f32_e32 v133, 0x4b800000, v132
	s_nop 0
	v_cndmask_b32_e32 v132, v132, v133, vcc
	v_rsq_f32_e32 v132, v132
	s_nop 0
	v_mul_f32_e32 v133, 0x45800000, v132
	v_cndmask_b32_e32 v132, v132, v133, vcc
	ds_write_b32 v0, v132 offset:4096

; __device__ __forceinline__ unsigned xb_ld(unsigned* p)              { return __hip_atomic_load(p, __ATOMIC_RELAXED, __HIP_MEMORY_SCOPE_AGENT); }
; __global__ void __launch_bounds__(512, 2) fwd_megakernel(Params p) {
;     ...
;         if (ph == 0) {
;             if (threadIdx.x == 0) {
;                 unsigned* bar = (unsigned*)(p.ws + W_BAR); bool ok = (gridDim.x & 7u) == 0u;
;                 for (unsigned j = 0; j < 16; ++j) { const unsigned c = xb_ld(&bar[XB_XCNT(j)]); ok = ok && (c == (j < 8 ? gridDim.x / 8u : 0u)); }
;                 if (ok) st[2] = st[3] * 8u + xb.x;
;             }
;             __syncthreads();
.LBB0_852:
	v_readlane_b32 s0, v245, 27
	v_readlane_b32 s1, v245, 28
	s_andn2_b64 vcc, exec, s[0:1]
	s_cbranch_vccnz .LBB0_21
	s_mov_b64 s[0:1], exec
	v_readlane_b32 s2, v247, 13
	v_readlane_b32 s3, v247, 14
	s_and_b64 s[2:3], s[0:1], s[2:3]
	s_mov_b64 exec, s[2:3]
	s_cbranch_execz .LBB0_20
	v_readlane_b32 s4, v246, 18
	v_readlane_b32 s36, v246, 19
	v_readlane_b32 s37, v246, 20
	v_readlane_b32 s38, v246, 21
	v_readlane_b32 s39, v246, 22
	v_readlane_b32 s40, v246, 23
	v_readlane_b32 s41, v246, 24
	v_readlane_b32 s42, v246, 25
	v_readlane_b32 s43, v246, 26
	v_readlane_b32 s44, v246, 27
	v_readlane_b32 s45, v246, 28
	v_readlane_b32 s46, v246, 29
	v_readlane_b32 s47, v246, 30
	v_readlane_b32 s48, v246, 31
	v_readlane_b32 s49, v246, 32
	v_readlane_b32 s50, v246, 33
	v_readlane_b32 s51, v246, 34
	s_nop 7
	global_load_dword v2, v1, s[36:37] sc1
	global_load_dword v3, v1, s[38:39] sc1
	global_load_dword v4, v1, s[40:41] sc1
	global_load_dword v5, v1, s[42:43] sc1
	global_load_dword v6, v1, s[44:45] sc1
	global_load_dword v7, v1, s[46:47] sc1
	global_load_dword v8, v1, s[48:49] sc1
	global_load_dword v9, v1, s[50:51] sc1
	s_nop 7
	v_readlane_b32 s36, v246, 35
	v_readlane_b32 s37, v246, 36
	v_readlane_b32 s38, v246, 37
	v_readlane_b32 s39, v246, 38
	v_readlane_b32 s40, v246, 39
	v_readlane_b32 s41, v246, 40
	v_readlane_b32 s42, v246, 41
	v_readlane_b32 s43, v246, 42
	v_readlane_b32 s44, v246, 43
	v_readlane_b32 s45, v246, 44
	v_readlane_b32 s46, v246, 45
	v_readlane_b32 s47, v246, 46
	v_readlane_b32 s48, v246, 47
	v_readlane_b32 s49, v246, 48
	v_readlane_b32 s50, v246, 49
	v_readlane_b32 s51, v246, 50
	s_nop 7
	global_load_dword v10, v1, s[36:37] sc1
	global_load_dword v11, v1, s[38:39] sc1
	global_load_dword v12, v1, s[40:41] sc1
	global_load_dword v13, v1, s[42:43] sc1
	global_load_dword v14, v1, s[44:45] sc1
	global_load_dword v15, v1, s[46:47] sc1
	global_load_dword v16, v1, s[48:49] sc1
	global_load_dword v17, v1, s[50:51] sc1
	s_nop 7
	v_readlane_b32 s2, v246, 16
	v_readlane_b32 s3, v246, 17
	s_waitcnt vmcnt(0)
	v_cmp_eq_u32_e32 vcc, s4, v2
	s_and_b64 s[2:3], s[2:3], vcc
	v_cmp_eq_u32_e32 vcc, s4, v3
	s_and_b64 s[2:3], s[2:3], vcc
	v_cmp_eq_u32_e32 vcc, s4, v4
	s_and_b64 s[2:3], s[2:3], vcc
	v_cmp_eq_u32_e32 vcc, s4, v5
	s_and_b64 s[2:3], s[2:3], vcc
	v_cmp_eq_u32_e32 vcc, s4, v6
	s_and_b64 s[2:3], s[2:3], vcc
	v_cmp_eq_u32_e32 vcc, s4, v7
	s_and_b64 s[2:3], s[2:3], vcc
	v_cmp_eq_u32_e32 vcc, s4, v8
	s_and_b64 s[2:3], s[2:3], vcc
	v_cmp_eq_u32_e32 vcc, s4, v9
	s_and_b64 s[2:3], s[2:3], vcc
	v_cmp_eq_u32_e32 vcc, 0, v10
	s_and_b64 s[2:3], s[2:3], vcc
	v_cmp_eq_u32_e32 vcc, 0, v11
	s_and_b64 s[2:3], s[2:3], vcc
	v_cmp_eq_u32_e32 vcc, 0, v12
	s_and_b64 s[2:3], s[2:3], vcc
	v_cmp_eq_u32_e32 vcc, 0, v13
	s_and_b64 s[2:3], s[2:3], vcc
	v_cmp_eq_u32_e32 vcc, 0, v14
	s_and_b64 s[2:3], s[2:3], vcc
	v_cmp_eq_u32_e32 vcc, 0, v15
	s_and_b64 s[2:3], s[2:3], vcc
	v_cmp_eq_u32_e32 vcc, 0, v16
	s_and_b64 s[2:3], s[2:3], vcc
	v_cmp_eq_u32_e32 vcc, 0, v17
	s_and_b64 s[2:3], s[2:3], vcc
	s_andn2_b64 vcc, exec, s[2:3]
	s_cbranch_vccnz .LBB0_20
	v_readlane_b32 s2, v246, 63
	s_nop 1
	v_mov_b32_e32 v0, s2
	ds_read_b32 v0, v0
	v_readlane_b32 s2, v247, 17
	s_waitcnt lgkmcnt(0)
	v_lshlrev_b32_e32 v0, 3, v0
	v_add_u32_e32 v0, s2, v0
	v_readlane_b32 s2, v246, 60
	s_nop 1
	v_mov_b32_e32 v2, s2
	ds_write_b32 v2, v0
	s_branch .LBB0_20
